# write-through (sc1) Z/LA stores in the in-projection epilogue so the L2 write-back at the following grid barrier has less to flush
# speedup vs baseline: 1.0217x; 1.0031x over previous
.LBB0_150:
	s_lshl_b32 s8, s35, 8
	s_add_i32 s8, s8, s47
	s_and_b32 s9, s54, -2
	s_cmp_eq_u32 s9, 4
	s_cselect_b64 s[10:11], -1, 0
	s_lshl_b32 s9, s34, 10
	v_mov_b32_e32 v132, v3
	v_mov_b32_e32 v133, v157
	s_add_i32 s9, s51, s9
	s_mov_b32 s23, 0xbfb8aa3b
	v_lshl_add_u32 v176, v132, 2, s9
	ds_read_b32 v170, v176
	v_add_u32_e32 v152, s8, v132
	v_ashrrev_i32_e32 v153, 31, v152
	s_mov_b32 s25, 0x3f317217
	s_mov_b32 s55, 0x7f800000
	s_mov_b32 s57, 0x42fc0000
	s_mov_b32 s56, 0x3e000000
	v_lshl_add_u32 v150, v133, 3, s48
	v_lshlrev_b64 v[154:155], 9, v[152:153]
	s_waitcnt lgkmcnt(0)
	v_pk_mul_f32 v[130:131], v[130:131], v[170:171] op_sel_hi:[1,0]
	v_pk_mul_f32 v[128:129], v[128:129], v[170:171] op_sel_hi:[1,0]
	v_pk_mul_f32 v[126:127], v[126:127], v[170:171] op_sel_hi:[1,0]
	v_pk_mul_f32 v[124:125], v[124:125], v[170:171] op_sel_hi:[1,0]
	s_mov_b64 s[34:35], -1
	s_mov_b64 s[30:31], 0
	s_cmp_lt_i32 s54, 9
	s_mov_b64 s[8:9], 0
	s_cbranch_scc1 .LBB0_154
	s_cmp_eq_u32 s54, 9
	s_mov_b64 s[8:9], -1
	s_cbranch_scc0 .LBB0_153
	v_ashrrev_i32_e32 v151, 31, v150
	v_lshl_add_u64 v[184:185], v[150:151], 2, s[18:19]
	global_load_dwordx4 v[192:195], v[184:185], off
	global_load_dwordx4 v[196:199], v[184:185], off offset:16
	global_load_dwordx4 v[200:203], v[184:185], off offset:512
	global_load_dwordx4 v[204:207], v[184:185], off offset:528
	v_mov_b32_e32 v228, 1.0
	v_mov_b32_e32 v229, 1.0
	v_mov_b32_e32 v230, 0x3f317217
	v_mov_b32_e32 v231, 0x3f317217
	v_mov_b32_e32 v232, 0x3377d1cf
	v_mov_b32_e32 v233, 0x3377d1cf
	v_mov_b32_e32 v234, 0x3d800000
	v_mov_b32_e32 v235, 0x3d800000
	s_waitcnt vmcnt(0)
	v_pk_add_f32 v[128:129], v[128:129], v[192:193]
	v_pk_add_f32 v[130:131], v[130:131], v[194:195]
	v_pk_add_f32 v[124:125], v[124:125], v[196:197]
	v_pk_add_f32 v[126:127], v[126:127], v[198:199]
	v_mul_f32_e64 v184, |v128|, s23
	v_mul_f32_e64 v185, |v129|, s23
	v_mul_f32_e64 v186, |v130|, s23
	v_mul_f32_e64 v187, |v131|, s23
	v_mul_f32_e64 v188, |v124|, s23
	v_mul_f32_e64 v189, |v125|, s23
	v_mul_f32_e64 v190, |v126|, s23
	v_mul_f32_e64 v191, |v127|, s23
	v_min_f32_e32 v128, 0, v128
	v_min_f32_e32 v129, 0, v129
	v_min_f32_e32 v130, 0, v130
	v_min_f32_e32 v131, 0, v131
	v_min_f32_e32 v124, 0, v124
	v_min_f32_e32 v125, 0, v125
	v_min_f32_e32 v126, 0, v126
	v_min_f32_e32 v127, 0, v127
	v_exp_f32_e32 v184, v184
	v_exp_f32_e32 v185, v185
	v_exp_f32_e32 v186, v186
	v_exp_f32_e32 v187, v187
	v_exp_f32_e32 v188, v188
	v_exp_f32_e32 v189, v189
	v_exp_f32_e32 v190, v190
	v_exp_f32_e32 v191, v191
	v_pk_add_f32 v[184:185], v[184:185], v[228:229]
	v_pk_add_f32 v[186:187], v[186:187], v[228:229]
	v_pk_add_f32 v[188:189], v[188:189], v[228:229]
	v_pk_add_f32 v[190:191], v[190:191], v[228:229]
	v_log_f32_e32 v184, v184
	v_log_f32_e32 v185, v185
	v_log_f32_e32 v186, v186
	v_log_f32_e32 v187, v187
	v_log_f32_e32 v188, v188
	v_log_f32_e32 v189, v189
	v_log_f32_e32 v190, v190
	v_log_f32_e32 v191, v191
	v_pk_mul_f32 v[220:221], v[230:231], v[184:185]
	v_pk_mul_f32 v[222:223], v[230:231], v[186:187]
	v_pk_mul_f32 v[224:225], v[230:231], v[188:189]
	v_pk_mul_f32 v[226:227], v[230:231], v[190:191]
	v_pk_fma_f32 v[220:221], v[184:185], v[230:231], v[220:221] neg_lo:[0,0,1] neg_hi:[0,0,1]
	v_pk_fma_f32 v[222:223], v[186:187], v[230:231], v[222:223] neg_lo:[0,0,1] neg_hi:[0,0,1]
	v_pk_fma_f32 v[224:225], v[188:189], v[230:231], v[224:225] neg_lo:[0,0,1] neg_hi:[0,0,1]
	v_pk_fma_f32 v[226:227], v[190:191], v[230:231], v[226:227] neg_lo:[0,0,1] neg_hi:[0,0,1]
	v_pk_fma_f32 v[220:221], v[232:233], v[184:185], v[220:221]
	v_pk_fma_f32 v[222:223], v[232:233], v[186:187], v[222:223]
	v_pk_fma_f32 v[224:225], v[232:233], v[188:189], v[224:225]
	v_pk_fma_f32 v[226:227], v[232:233], v[190:191], v[226:227]
	v_pk_fma_f32 v[220:221], v[230:231], v[184:185], v[220:221]
	v_pk_fma_f32 v[222:223], v[230:231], v[186:187], v[222:223]
	v_pk_fma_f32 v[224:225], v[230:231], v[188:189], v[224:225]
	v_pk_fma_f32 v[226:227], v[230:231], v[190:191], v[226:227]
	v_pk_add_f32 v[128:129], v[128:129], v[220:221] neg_lo:[0,1] neg_hi:[0,1]
	v_pk_add_f32 v[130:131], v[130:131], v[222:223] neg_lo:[0,1] neg_hi:[0,1]
	v_pk_add_f32 v[124:125], v[124:125], v[224:225] neg_lo:[0,1] neg_hi:[0,1]
	v_pk_add_f32 v[126:127], v[126:127], v[226:227] neg_lo:[0,1] neg_hi:[0,1]
	v_pk_mul_f32 v[128:129], v[234:235], v[128:129]
	v_pk_mul_f32 v[130:131], v[234:235], v[130:131]
	v_pk_mul_f32 v[124:125], v[234:235], v[124:125]
	v_pk_mul_f32 v[126:127], v[234:235], v[126:127]
	v_cvt_pk_bf16_f32 v134, v128, v129
	v_cvt_pk_bf16_f32 v135, v130, v131
	v_cvt_pk_bf16_f32 v136, v124, v125
	v_cvt_pk_bf16_f32 v137, v126, v127
	v_lshl_add_u64 v[132:133], s[16:17], 0, v[154:155]
	v_lshl_add_u64 v[132:133], v[150:151], 1, v[132:133]
	global_store_dwordx4 v[132:133], v[134:137], off sc1
	s_mov_b64 s[8:9], 0

.LBB0_162:
	s_lshl_b32 s30, s54, 8
	v_mad_i64_i32 v[124:125], s[10:11], v152, s62, 0
	s_ashr_i32 s31, s30, 31
	v_lshl_add_u64 v[124:125], s[14:15], 0, v[124:125]
	s_andn2_b64 vcc, exec, s[34:35]
	v_ashrrev_i32_e32 v151, 31, v150
	v_lshl_add_u64 v[172:173], s[30:31], 1, v[124:125]
	s_cbranch_vccnz .LBB0_164
	v_lshl_add_u64 v[128:129], v[150:151], 1, v[172:173]
	v_cvt_pk_bf16_f32 v124, v132, v133
	v_cvt_pk_bf16_f32 v125, v134, v135
	v_cvt_pk_bf16_f32 v126, v136, v137
	v_cvt_pk_bf16_f32 v127, v138, v139
	global_store_dwordx4 v[128:129], v[124:127], off sc1
.LBB0_164:
	v_mov_b32_e32 v171, v170
	s_nop 0
	v_mov_b32_e32 v124, v170
	v_mov_b32_e32 v125, v170
	v_pk_mul_f32 v[122:123], v[122:123], v[124:125]
	v_pk_mul_f32 v[120:121], v[120:121], v[170:171]
	v_pk_mul_f32 v[118:119], v[118:119], v[124:125]
	v_pk_mul_f32 v[116:117], v[116:117], v[170:171]
	s_mov_b64 s[36:37], -1
	s_mov_b64 s[34:35], 0
	s_cmp_lt_i32 s54, 9
	s_mov_b64 s[10:11], 0
	s_cbranch_scc1 .LBB0_168
	s_cmp_eq_u32 s54, 9
	s_mov_b64 s[10:11], -1
	s_cbranch_scc0 .LBB0_167
	v_pk_add_f32 v[120:121], v[120:121], v[200:201]
	v_pk_add_f32 v[122:123], v[122:123], v[202:203]
	v_pk_add_f32 v[116:117], v[116:117], v[204:205]
	v_pk_add_f32 v[118:119], v[118:119], v[206:207]
	v_mul_f32_e64 v184, |v120|, s23
	v_mul_f32_e64 v185, |v121|, s23
	v_mul_f32_e64 v186, |v122|, s23
	v_mul_f32_e64 v187, |v123|, s23
	v_mul_f32_e64 v188, |v116|, s23
	v_mul_f32_e64 v189, |v117|, s23
	v_mul_f32_e64 v190, |v118|, s23
	v_mul_f32_e64 v191, |v119|, s23
	v_min_f32_e32 v120, 0, v120
	v_min_f32_e32 v121, 0, v121
	v_min_f32_e32 v122, 0, v122
	v_min_f32_e32 v123, 0, v123
	v_min_f32_e32 v116, 0, v116
	v_min_f32_e32 v117, 0, v117
	v_min_f32_e32 v118, 0, v118
	v_min_f32_e32 v119, 0, v119
	v_exp_f32_e32 v184, v184
	v_exp_f32_e32 v185, v185
	v_exp_f32_e32 v186, v186
	v_exp_f32_e32 v187, v187
	v_exp_f32_e32 v188, v188
	v_exp_f32_e32 v189, v189
	v_exp_f32_e32 v190, v190
	v_exp_f32_e32 v191, v191
	v_pk_add_f32 v[184:185], v[184:185], v[228:229]
	v_pk_add_f32 v[186:187], v[186:187], v[228:229]
	v_pk_add_f32 v[188:189], v[188:189], v[228:229]
	v_pk_add_f32 v[190:191], v[190:191], v[228:229]
	v_log_f32_e32 v184, v184
	v_log_f32_e32 v185, v185
	v_log_f32_e32 v186, v186
	v_log_f32_e32 v187, v187
	v_log_f32_e32 v188, v188
	v_log_f32_e32 v189, v189
	v_log_f32_e32 v190, v190
	v_log_f32_e32 v191, v191
	v_pk_mul_f32 v[220:221], v[230:231], v[184:185]
	v_pk_mul_f32 v[222:223], v[230:231], v[186:187]
	v_pk_mul_f32 v[224:225], v[230:231], v[188:189]
	v_pk_mul_f32 v[226:227], v[230:231], v[190:191]
	v_pk_fma_f32 v[220:221], v[184:185], v[230:231], v[220:221] neg_lo:[0,0,1] neg_hi:[0,0,1]
	v_pk_fma_f32 v[222:223], v[186:187], v[230:231], v[222:223] neg_lo:[0,0,1] neg_hi:[0,0,1]
	v_pk_fma_f32 v[224:225], v[188:189], v[230:231], v[224:225] neg_lo:[0,0,1] neg_hi:[0,0,1]
	v_pk_fma_f32 v[226:227], v[190:191], v[230:231], v[226:227] neg_lo:[0,0,1] neg_hi:[0,0,1]
	v_pk_fma_f32 v[220:221], v[232:233], v[184:185], v[220:221]
	v_pk_fma_f32 v[222:223], v[232:233], v[186:187], v[222:223]
	v_pk_fma_f32 v[224:225], v[232:233], v[188:189], v[224:225]
	v_pk_fma_f32 v[226:227], v[232:233], v[190:191], v[226:227]
	v_pk_fma_f32 v[220:221], v[230:231], v[184:185], v[220:221]
	v_pk_fma_f32 v[222:223], v[230:231], v[186:187], v[222:223]
	v_pk_fma_f32 v[224:225], v[230:231], v[188:189], v[224:225]
	v_pk_fma_f32 v[226:227], v[230:231], v[190:191], v[226:227]
	v_pk_add_f32 v[120:121], v[120:121], v[220:221] neg_lo:[0,1] neg_hi:[0,1]
	v_pk_add_f32 v[122:123], v[122:123], v[222:223] neg_lo:[0,1] neg_hi:[0,1]
	v_pk_add_f32 v[116:117], v[116:117], v[224:225] neg_lo:[0,1] neg_hi:[0,1]
	v_pk_add_f32 v[118:119], v[118:119], v[226:227] neg_lo:[0,1] neg_hi:[0,1]
	v_pk_mul_f32 v[120:121], v[234:235], v[120:121]
	v_pk_mul_f32 v[122:123], v[234:235], v[122:123]
	v_pk_mul_f32 v[116:117], v[234:235], v[116:117]
	v_pk_mul_f32 v[118:119], v[234:235], v[118:119]
	v_cvt_pk_bf16_f32 v126, v120, v121
	v_cvt_pk_bf16_f32 v127, v122, v123
	v_cvt_pk_bf16_f32 v128, v116, v117
	v_cvt_pk_bf16_f32 v129, v118, v119
	v_lshl_add_u64 v[124:125], s[16:17], 0, v[154:155]
	v_lshl_add_u64 v[124:125], v[150:151], 1, v[124:125]
	global_store_dwordx4 v[124:125], v[126:129], off offset:256 sc1
	s_mov_b64 s[10:11], 0

.LBB0_175:
	v_lshl_add_u64 v[120:121], v[150:151], 1, v[172:173]
	v_cvt_pk_bf16_f32 v116, v124, v125
	v_cvt_pk_bf16_f32 v117, v126, v127
	v_cvt_pk_bf16_f32 v118, v128, v129
	v_cvt_pk_bf16_f32 v119, v130, v131
	global_store_dwordx4 v[120:121], v[116:119], off offset:256 sc1
.LBB0_176:
	ds_read_b32 v126, v176 offset:64
	v_add_u32_e32 v128, 16, v152
	v_ashrrev_i32_e32 v129, 31, v128
	v_lshlrev_b64 v[124:125], 9, v[128:129]
	s_mov_b64 s[36:37], -1
	s_waitcnt lgkmcnt(0)
	v_pk_mul_f32 v[114:115], v[114:115], v[126:127] op_sel_hi:[1,0]
	v_pk_mul_f32 v[112:113], v[112:113], v[126:127] op_sel_hi:[1,0]
	v_pk_mul_f32 v[110:111], v[110:111], v[126:127] op_sel_hi:[1,0]
	v_pk_mul_f32 v[108:109], v[108:109], v[126:127] op_sel_hi:[1,0]
	s_mov_b64 s[34:35], 0
	s_cmp_lt_i32 s54, 9
	s_mov_b64 s[10:11], 0
	s_cbranch_scc1 .LBB0_182
	s_cmp_eq_u32 s54, 9
	s_mov_b64 s[10:11], -1
	s_cbranch_scc0 .LBB0_179
	v_pk_add_f32 v[112:113], v[112:113], v[192:193]
	v_pk_add_f32 v[114:115], v[114:115], v[194:195]
	v_pk_add_f32 v[108:109], v[108:109], v[196:197]
	v_pk_add_f32 v[110:111], v[110:111], v[198:199]
	v_mul_f32_e64 v184, |v112|, s23
	v_mul_f32_e64 v185, |v113|, s23
	v_mul_f32_e64 v186, |v114|, s23
	v_mul_f32_e64 v187, |v115|, s23
	v_mul_f32_e64 v188, |v108|, s23
	v_mul_f32_e64 v189, |v109|, s23
	v_mul_f32_e64 v190, |v110|, s23
	v_mul_f32_e64 v191, |v111|, s23
	v_min_f32_e32 v112, 0, v112
	v_min_f32_e32 v113, 0, v113
	v_min_f32_e32 v114, 0, v114
	v_min_f32_e32 v115, 0, v115
	v_min_f32_e32 v108, 0, v108
	v_min_f32_e32 v109, 0, v109
	v_min_f32_e32 v110, 0, v110
	v_min_f32_e32 v111, 0, v111
	v_exp_f32_e32 v184, v184
	v_exp_f32_e32 v185, v185
	v_exp_f32_e32 v186, v186
	v_exp_f32_e32 v187, v187
	v_exp_f32_e32 v188, v188
	v_exp_f32_e32 v189, v189
	v_exp_f32_e32 v190, v190
	v_exp_f32_e32 v191, v191
	v_pk_add_f32 v[184:185], v[184:185], v[228:229]
	v_pk_add_f32 v[186:187], v[186:187], v[228:229]
	v_pk_add_f32 v[188:189], v[188:189], v[228:229]
	v_pk_add_f32 v[190:191], v[190:191], v[228:229]
	v_log_f32_e32 v184, v184
	v_log_f32_e32 v185, v185
	v_log_f32_e32 v186, v186
	v_log_f32_e32 v187, v187
	v_log_f32_e32 v188, v188
	v_log_f32_e32 v189, v189
	v_log_f32_e32 v190, v190
	v_log_f32_e32 v191, v191
	v_pk_mul_f32 v[220:221], v[230:231], v[184:185]
	v_pk_mul_f32 v[222:223], v[230:231], v[186:187]
	v_pk_mul_f32 v[224:225], v[230:231], v[188:189]
	v_pk_mul_f32 v[226:227], v[230:231], v[190:191]
	v_pk_fma_f32 v[220:221], v[184:185], v[230:231], v[220:221] neg_lo:[0,0,1] neg_hi:[0,0,1]
	v_pk_fma_f32 v[222:223], v[186:187], v[230:231], v[222:223] neg_lo:[0,0,1] neg_hi:[0,0,1]
	v_pk_fma_f32 v[224:225], v[188:189], v[230:231], v[224:225] neg_lo:[0,0,1] neg_hi:[0,0,1]
	v_pk_fma_f32 v[226:227], v[190:191], v[230:231], v[226:227] neg_lo:[0,0,1] neg_hi:[0,0,1]
	v_pk_fma_f32 v[220:221], v[232:233], v[184:185], v[220:221]
	v_pk_fma_f32 v[222:223], v[232:233], v[186:187], v[222:223]
	v_pk_fma_f32 v[224:225], v[232:233], v[188:189], v[224:225]
	v_pk_fma_f32 v[226:227], v[232:233], v[190:191], v[226:227]
	v_pk_fma_f32 v[220:221], v[230:231], v[184:185], v[220:221]
	v_pk_fma_f32 v[222:223], v[230:231], v[186:187], v[222:223]
	v_pk_fma_f32 v[224:225], v[230:231], v[188:189], v[224:225]
	v_pk_fma_f32 v[226:227], v[230:231], v[190:191], v[226:227]
	v_pk_add_f32 v[112:113], v[112:113], v[220:221] neg_lo:[0,1] neg_hi:[0,1]
	v_pk_add_f32 v[114:115], v[114:115], v[222:223] neg_lo:[0,1] neg_hi:[0,1]
	v_pk_add_f32 v[108:109], v[108:109], v[224:225] neg_lo:[0,1] neg_hi:[0,1]
	v_pk_add_f32 v[110:111], v[110:111], v[226:227] neg_lo:[0,1] neg_hi:[0,1]
	v_pk_mul_f32 v[112:113], v[234:235], v[112:113]
	v_pk_mul_f32 v[114:115], v[234:235], v[114:115]
	v_pk_mul_f32 v[108:109], v[234:235], v[108:109]
	v_pk_mul_f32 v[110:111], v[234:235], v[110:111]
	v_cvt_pk_bf16_f32 v118, v112, v113
	v_cvt_pk_bf16_f32 v119, v114, v115
	v_cvt_pk_bf16_f32 v120, v108, v109
	v_cvt_pk_bf16_f32 v121, v110, v111
	v_lshl_add_u64 v[116:117], s[16:17], 0, v[124:125]
	v_lshl_add_u64 v[116:117], v[150:151], 1, v[116:117]
	global_store_dwordx4 v[116:117], v[118:121], off sc1
	s_mov_b64 s[10:11], 0

.LBB0_190:
	v_mad_i64_i32 v[108:109], s[34:35], v128, s62, 0
	v_lshl_add_u64 v[108:109], s[14:15], 0, v[108:109]
	s_andn2_b64 vcc, exec, s[10:11]
	v_lshl_add_u64 v[128:129], s[30:31], 1, v[108:109]
	s_cbranch_vccnz .LBB0_192
	v_lshl_add_u64 v[112:113], v[150:151], 1, v[128:129]
	v_cvt_pk_bf16_f32 v108, v116, v117
	v_cvt_pk_bf16_f32 v109, v118, v119
	v_cvt_pk_bf16_f32 v110, v120, v121
	v_cvt_pk_bf16_f32 v111, v122, v123
	global_store_dwordx4 v[112:113], v[108:111], off sc1
.LBB0_192:
	v_mov_b32_e32 v127, v126
	s_nop 0
	v_mov_b32_e32 v108, v126
	v_mov_b32_e32 v109, v126
	v_pk_mul_f32 v[106:107], v[106:107], v[108:109]
	v_pk_mul_f32 v[104:105], v[104:105], v[126:127]
	v_pk_mul_f32 v[102:103], v[102:103], v[108:109]
	v_pk_mul_f32 v[100:101], v[100:101], v[126:127]
	s_mov_b64 s[36:37], -1
	s_mov_b64 s[34:35], 0
	s_cmp_lt_i32 s54, 9
	s_mov_b64 s[10:11], 0
	s_cbranch_scc1 .LBB0_196
	s_cmp_eq_u32 s54, 9
	s_mov_b64 s[10:11], -1
	s_cbranch_scc0 .LBB0_195
	v_pk_add_f32 v[104:105], v[104:105], v[200:201]
	v_pk_add_f32 v[106:107], v[106:107], v[202:203]
	v_pk_add_f32 v[100:101], v[100:101], v[204:205]
	v_pk_add_f32 v[102:103], v[102:103], v[206:207]
	v_mul_f32_e64 v184, |v104|, s23
	v_mul_f32_e64 v185, |v105|, s23
	v_mul_f32_e64 v186, |v106|, s23
	v_mul_f32_e64 v187, |v107|, s23
	v_mul_f32_e64 v188, |v100|, s23
	v_mul_f32_e64 v189, |v101|, s23
	v_mul_f32_e64 v190, |v102|, s23
	v_mul_f32_e64 v191, |v103|, s23
	v_min_f32_e32 v104, 0, v104
	v_min_f32_e32 v105, 0, v105
	v_min_f32_e32 v106, 0, v106
	v_min_f32_e32 v107, 0, v107
	v_min_f32_e32 v100, 0, v100
	v_min_f32_e32 v101, 0, v101
	v_min_f32_e32 v102, 0, v102
	v_min_f32_e32 v103, 0, v103
	v_exp_f32_e32 v184, v184
	v_exp_f32_e32 v185, v185
	v_exp_f32_e32 v186, v186
	v_exp_f32_e32 v187, v187
	v_exp_f32_e32 v188, v188
	v_exp_f32_e32 v189, v189
	v_exp_f32_e32 v190, v190
	v_exp_f32_e32 v191, v191
	v_pk_add_f32 v[184:185], v[184:185], v[228:229]
	v_pk_add_f32 v[186:187], v[186:187], v[228:229]
	v_pk_add_f32 v[188:189], v[188:189], v[228:229]
	v_pk_add_f32 v[190:191], v[190:191], v[228:229]
	v_log_f32_e32 v184, v184
	v_log_f32_e32 v185, v185
	v_log_f32_e32 v186, v186
	v_log_f32_e32 v187, v187
	v_log_f32_e32 v188, v188
	v_log_f32_e32 v189, v189
	v_log_f32_e32 v190, v190
	v_log_f32_e32 v191, v191
	v_pk_mul_f32 v[220:221], v[230:231], v[184:185]
	v_pk_mul_f32 v[222:223], v[230:231], v[186:187]
	v_pk_mul_f32 v[224:225], v[230:231], v[188:189]
	v_pk_mul_f32 v[226:227], v[230:231], v[190:191]
	v_pk_fma_f32 v[220:221], v[184:185], v[230:231], v[220:221] neg_lo:[0,0,1] neg_hi:[0,0,1]
	v_pk_fma_f32 v[222:223], v[186:187], v[230:231], v[222:223] neg_lo:[0,0,1] neg_hi:[0,0,1]
	v_pk_fma_f32 v[224:225], v[188:189], v[230:231], v[224:225] neg_lo:[0,0,1] neg_hi:[0,0,1]
	v_pk_fma_f32 v[226:227], v[190:191], v[230:231], v[226:227] neg_lo:[0,0,1] neg_hi:[0,0,1]
	v_pk_fma_f32 v[220:221], v[232:233], v[184:185], v[220:221]
	v_pk_fma_f32 v[222:223], v[232:233], v[186:187], v[222:223]
	v_pk_fma_f32 v[224:225], v[232:233], v[188:189], v[224:225]
	v_pk_fma_f32 v[226:227], v[232:233], v[190:191], v[226:227]
	v_pk_fma_f32 v[220:221], v[230:231], v[184:185], v[220:221]
	v_pk_fma_f32 v[222:223], v[230:231], v[186:187], v[222:223]
	v_pk_fma_f32 v[224:225], v[230:231], v[188:189], v[224:225]
	v_pk_fma_f32 v[226:227], v[230:231], v[190:191], v[226:227]
	v_pk_add_f32 v[104:105], v[104:105], v[220:221] neg_lo:[0,1] neg_hi:[0,1]
	v_pk_add_f32 v[106:107], v[106:107], v[222:223] neg_lo:[0,1] neg_hi:[0,1]
	v_pk_add_f32 v[100:101], v[100:101], v[224:225] neg_lo:[0,1] neg_hi:[0,1]
	v_pk_add_f32 v[102:103], v[102:103], v[226:227] neg_lo:[0,1] neg_hi:[0,1]
	v_pk_mul_f32 v[104:105], v[234:235], v[104:105]
	v_pk_mul_f32 v[106:107], v[234:235], v[106:107]
	v_pk_mul_f32 v[100:101], v[234:235], v[100:101]
	v_pk_mul_f32 v[102:103], v[234:235], v[102:103]
	v_cvt_pk_bf16_f32 v110, v104, v105
	v_cvt_pk_bf16_f32 v111, v106, v107
	v_cvt_pk_bf16_f32 v112, v100, v101
	v_cvt_pk_bf16_f32 v113, v102, v103
	v_lshl_add_u64 v[108:109], s[16:17], 0, v[124:125]
	v_lshl_add_u64 v[108:109], v[150:151], 1, v[108:109]
	global_store_dwordx4 v[108:109], v[110:113], off offset:256 sc1
	s_mov_b64 s[10:11], 0

.LBB0_203:
	v_lshl_add_u64 v[104:105], v[150:151], 1, v[128:129]
	v_cvt_pk_bf16_f32 v100, v108, v109
	v_cvt_pk_bf16_f32 v101, v110, v111
	v_cvt_pk_bf16_f32 v102, v112, v113
	v_cvt_pk_bf16_f32 v103, v114, v115
	global_store_dwordx4 v[104:105], v[100:103], off offset:256 sc1
.LBB0_204:
	ds_read_b32 v110, v176 offset:128
	v_add_u32_e32 v112, 32, v152
	v_ashrrev_i32_e32 v113, 31, v112
	v_lshlrev_b64 v[108:109], 9, v[112:113]
	s_mov_b64 s[36:37], -1
	s_waitcnt lgkmcnt(0)
	v_pk_mul_f32 v[98:99], v[98:99], v[110:111] op_sel_hi:[1,0]
	v_pk_mul_f32 v[96:97], v[96:97], v[110:111] op_sel_hi:[1,0]
	v_pk_mul_f32 v[94:95], v[94:95], v[110:111] op_sel_hi:[1,0]
	v_pk_mul_f32 v[92:93], v[92:93], v[110:111] op_sel_hi:[1,0]
	s_mov_b64 s[34:35], 0
	s_cmp_lt_i32 s54, 9
	s_mov_b64 s[10:11], 0
	s_cbranch_scc1 .LBB0_210
	s_cmp_eq_u32 s54, 9
	s_mov_b64 s[10:11], -1
	s_cbranch_scc0 .LBB0_207
	v_pk_add_f32 v[96:97], v[96:97], v[192:193]
	v_pk_add_f32 v[98:99], v[98:99], v[194:195]
	v_pk_add_f32 v[92:93], v[92:93], v[196:197]
	v_pk_add_f32 v[94:95], v[94:95], v[198:199]
	v_mul_f32_e64 v184, |v96|, s23
	v_mul_f32_e64 v185, |v97|, s23
	v_mul_f32_e64 v186, |v98|, s23
	v_mul_f32_e64 v187, |v99|, s23
	v_mul_f32_e64 v188, |v92|, s23
	v_mul_f32_e64 v189, |v93|, s23
	v_mul_f32_e64 v190, |v94|, s23
	v_mul_f32_e64 v191, |v95|, s23
	v_min_f32_e32 v96, 0, v96
	v_min_f32_e32 v97, 0, v97
	v_min_f32_e32 v98, 0, v98
	v_min_f32_e32 v99, 0, v99
	v_min_f32_e32 v92, 0, v92
	v_min_f32_e32 v93, 0, v93
	v_min_f32_e32 v94, 0, v94
	v_min_f32_e32 v95, 0, v95
	v_exp_f32_e32 v184, v184
	v_exp_f32_e32 v185, v185
	v_exp_f32_e32 v186, v186
	v_exp_f32_e32 v187, v187
	v_exp_f32_e32 v188, v188
	v_exp_f32_e32 v189, v189
	v_exp_f32_e32 v190, v190
	v_exp_f32_e32 v191, v191
	v_pk_add_f32 v[184:185], v[184:185], v[228:229]
	v_pk_add_f32 v[186:187], v[186:187], v[228:229]
	v_pk_add_f32 v[188:189], v[188:189], v[228:229]
	v_pk_add_f32 v[190:191], v[190:191], v[228:229]
	v_log_f32_e32 v184, v184
	v_log_f32_e32 v185, v185
	v_log_f32_e32 v186, v186
	v_log_f32_e32 v187, v187
	v_log_f32_e32 v188, v188
	v_log_f32_e32 v189, v189
	v_log_f32_e32 v190, v190
	v_log_f32_e32 v191, v191
	v_pk_mul_f32 v[220:221], v[230:231], v[184:185]
	v_pk_mul_f32 v[222:223], v[230:231], v[186:187]
	v_pk_mul_f32 v[224:225], v[230:231], v[188:189]
	v_pk_mul_f32 v[226:227], v[230:231], v[190:191]
	v_pk_fma_f32 v[220:221], v[184:185], v[230:231], v[220:221] neg_lo:[0,0,1] neg_hi:[0,0,1]
	v_pk_fma_f32 v[222:223], v[186:187], v[230:231], v[222:223] neg_lo:[0,0,1] neg_hi:[0,0,1]
	v_pk_fma_f32 v[224:225], v[188:189], v[230:231], v[224:225] neg_lo:[0,0,1] neg_hi:[0,0,1]
	v_pk_fma_f32 v[226:227], v[190:191], v[230:231], v[226:227] neg_lo:[0,0,1] neg_hi:[0,0,1]
	v_pk_fma_f32 v[220:221], v[232:233], v[184:185], v[220:221]
	v_pk_fma_f32 v[222:223], v[232:233], v[186:187], v[222:223]
	v_pk_fma_f32 v[224:225], v[232:233], v[188:189], v[224:225]
	v_pk_fma_f32 v[226:227], v[232:233], v[190:191], v[226:227]
	v_pk_fma_f32 v[220:221], v[230:231], v[184:185], v[220:221]
	v_pk_fma_f32 v[222:223], v[230:231], v[186:187], v[222:223]
	v_pk_fma_f32 v[224:225], v[230:231], v[188:189], v[224:225]
	v_pk_fma_f32 v[226:227], v[230:231], v[190:191], v[226:227]
	v_pk_add_f32 v[96:97], v[96:97], v[220:221] neg_lo:[0,1] neg_hi:[0,1]
	v_pk_add_f32 v[98:99], v[98:99], v[222:223] neg_lo:[0,1] neg_hi:[0,1]
	v_pk_add_f32 v[92:93], v[92:93], v[224:225] neg_lo:[0,1] neg_hi:[0,1]
	v_pk_add_f32 v[94:95], v[94:95], v[226:227] neg_lo:[0,1] neg_hi:[0,1]
	v_pk_mul_f32 v[96:97], v[234:235], v[96:97]
	v_pk_mul_f32 v[98:99], v[234:235], v[98:99]
	v_pk_mul_f32 v[92:93], v[234:235], v[92:93]
	v_pk_mul_f32 v[94:95], v[234:235], v[94:95]
	v_cvt_pk_bf16_f32 v102, v96, v97
	v_cvt_pk_bf16_f32 v103, v98, v99
	v_cvt_pk_bf16_f32 v104, v92, v93
	v_cvt_pk_bf16_f32 v105, v94, v95
	v_lshl_add_u64 v[100:101], s[16:17], 0, v[108:109]
	v_lshl_add_u64 v[100:101], v[150:151], 1, v[100:101]
	global_store_dwordx4 v[100:101], v[102:105], off sc1
	s_mov_b64 s[10:11], 0

.LBB0_218:
	v_mad_i64_i32 v[92:93], s[34:35], v112, s62, 0
	v_lshl_add_u64 v[92:93], s[14:15], 0, v[92:93]
	s_andn2_b64 vcc, exec, s[10:11]
	v_lshl_add_u64 v[112:113], s[30:31], 1, v[92:93]
	s_cbranch_vccnz .LBB0_220
	v_lshl_add_u64 v[96:97], v[150:151], 1, v[112:113]
	v_cvt_pk_bf16_f32 v92, v100, v101
	v_cvt_pk_bf16_f32 v93, v102, v103
	v_cvt_pk_bf16_f32 v94, v104, v105
	v_cvt_pk_bf16_f32 v95, v106, v107
	global_store_dwordx4 v[96:97], v[92:95], off sc1
.LBB0_220:
	v_mov_b32_e32 v111, v110
	s_nop 0
	v_mov_b32_e32 v92, v110
	v_mov_b32_e32 v93, v110
	v_pk_mul_f32 v[90:91], v[90:91], v[92:93]
	v_pk_mul_f32 v[88:89], v[88:89], v[110:111]
	v_pk_mul_f32 v[86:87], v[86:87], v[92:93]
	v_pk_mul_f32 v[84:85], v[84:85], v[110:111]
	s_mov_b64 s[36:37], -1
	s_mov_b64 s[34:35], 0
	s_cmp_lt_i32 s54, 9
	s_mov_b64 s[10:11], 0
	s_cbranch_scc1 .LBB0_224
	s_cmp_eq_u32 s54, 9
	s_mov_b64 s[10:11], -1
	s_cbranch_scc0 .LBB0_223
	v_pk_add_f32 v[88:89], v[88:89], v[200:201]
	v_pk_add_f32 v[90:91], v[90:91], v[202:203]
	v_pk_add_f32 v[84:85], v[84:85], v[204:205]
	v_pk_add_f32 v[86:87], v[86:87], v[206:207]
	v_mul_f32_e64 v184, |v88|, s23
	v_mul_f32_e64 v185, |v89|, s23
	v_mul_f32_e64 v186, |v90|, s23
	v_mul_f32_e64 v187, |v91|, s23
	v_mul_f32_e64 v188, |v84|, s23
	v_mul_f32_e64 v189, |v85|, s23
	v_mul_f32_e64 v190, |v86|, s23
	v_mul_f32_e64 v191, |v87|, s23
	v_min_f32_e32 v88, 0, v88
	v_min_f32_e32 v89, 0, v89
	v_min_f32_e32 v90, 0, v90
	v_min_f32_e32 v91, 0, v91
	v_min_f32_e32 v84, 0, v84
	v_min_f32_e32 v85, 0, v85
	v_min_f32_e32 v86, 0, v86
	v_min_f32_e32 v87, 0, v87
	v_exp_f32_e32 v184, v184
	v_exp_f32_e32 v185, v185
	v_exp_f32_e32 v186, v186
	v_exp_f32_e32 v187, v187
	v_exp_f32_e32 v188, v188
	v_exp_f32_e32 v189, v189
	v_exp_f32_e32 v190, v190
	v_exp_f32_e32 v191, v191
	v_pk_add_f32 v[184:185], v[184:185], v[228:229]
	v_pk_add_f32 v[186:187], v[186:187], v[228:229]
	v_pk_add_f32 v[188:189], v[188:189], v[228:229]
	v_pk_add_f32 v[190:191], v[190:191], v[228:229]
	v_log_f32_e32 v184, v184
	v_log_f32_e32 v185, v185
	v_log_f32_e32 v186, v186
	v_log_f32_e32 v187, v187
	v_log_f32_e32 v188, v188
	v_log_f32_e32 v189, v189
	v_log_f32_e32 v190, v190
	v_log_f32_e32 v191, v191
	v_pk_mul_f32 v[220:221], v[230:231], v[184:185]
	v_pk_mul_f32 v[222:223], v[230:231], v[186:187]
	v_pk_mul_f32 v[224:225], v[230:231], v[188:189]
	v_pk_mul_f32 v[226:227], v[230:231], v[190:191]
	v_pk_fma_f32 v[220:221], v[184:185], v[230:231], v[220:221] neg_lo:[0,0,1] neg_hi:[0,0,1]
	v_pk_fma_f32 v[222:223], v[186:187], v[230:231], v[222:223] neg_lo:[0,0,1] neg_hi:[0,0,1]
	v_pk_fma_f32 v[224:225], v[188:189], v[230:231], v[224:225] neg_lo:[0,0,1] neg_hi:[0,0,1]
	v_pk_fma_f32 v[226:227], v[190:191], v[230:231], v[226:227] neg_lo:[0,0,1] neg_hi:[0,0,1]
	v_pk_fma_f32 v[220:221], v[232:233], v[184:185], v[220:221]
	v_pk_fma_f32 v[222:223], v[232:233], v[186:187], v[222:223]
	v_pk_fma_f32 v[224:225], v[232:233], v[188:189], v[224:225]
	v_pk_fma_f32 v[226:227], v[232:233], v[190:191], v[226:227]
	v_pk_fma_f32 v[220:221], v[230:231], v[184:185], v[220:221]
	v_pk_fma_f32 v[222:223], v[230:231], v[186:187], v[222:223]
	v_pk_fma_f32 v[224:225], v[230:231], v[188:189], v[224:225]
	v_pk_fma_f32 v[226:227], v[230:231], v[190:191], v[226:227]
	v_pk_add_f32 v[88:89], v[88:89], v[220:221] neg_lo:[0,1] neg_hi:[0,1]
	v_pk_add_f32 v[90:91], v[90:91], v[222:223] neg_lo:[0,1] neg_hi:[0,1]
	v_pk_add_f32 v[84:85], v[84:85], v[224:225] neg_lo:[0,1] neg_hi:[0,1]
	v_pk_add_f32 v[86:87], v[86:87], v[226:227] neg_lo:[0,1] neg_hi:[0,1]
	v_pk_mul_f32 v[88:89], v[234:235], v[88:89]
	v_pk_mul_f32 v[90:91], v[234:235], v[90:91]
	v_pk_mul_f32 v[84:85], v[234:235], v[84:85]
	v_pk_mul_f32 v[86:87], v[234:235], v[86:87]
	v_cvt_pk_bf16_f32 v94, v88, v89
	v_cvt_pk_bf16_f32 v95, v90, v91
	v_cvt_pk_bf16_f32 v96, v84, v85
	v_cvt_pk_bf16_f32 v97, v86, v87
	v_lshl_add_u64 v[92:93], s[16:17], 0, v[108:109]
	v_lshl_add_u64 v[92:93], v[150:151], 1, v[92:93]
	global_store_dwordx4 v[92:93], v[94:97], off offset:256 sc1
	s_mov_b64 s[10:11], 0

.LBB0_231:
	v_lshl_add_u64 v[88:89], v[150:151], 1, v[112:113]
	v_cvt_pk_bf16_f32 v84, v92, v93
	v_cvt_pk_bf16_f32 v85, v94, v95
	v_cvt_pk_bf16_f32 v86, v96, v97
	v_cvt_pk_bf16_f32 v87, v98, v99
	global_store_dwordx4 v[88:89], v[84:87], off offset:256 sc1
.LBB0_232:
	ds_read_b32 v94, v176 offset:192
	v_add_u32_e32 v96, 48, v152
	v_ashrrev_i32_e32 v97, 31, v96
	v_lshlrev_b64 v[92:93], 9, v[96:97]
	s_mov_b64 s[36:37], -1
	s_waitcnt lgkmcnt(0)
	v_pk_mul_f32 v[82:83], v[82:83], v[94:95] op_sel_hi:[1,0]
	v_pk_mul_f32 v[80:81], v[80:81], v[94:95] op_sel_hi:[1,0]
	v_pk_mul_f32 v[78:79], v[78:79], v[94:95] op_sel_hi:[1,0]
	v_pk_mul_f32 v[76:77], v[76:77], v[94:95] op_sel_hi:[1,0]
	s_mov_b64 s[34:35], 0
	s_cmp_lt_i32 s54, 9
	s_mov_b64 s[10:11], 0
	s_cbranch_scc1 .LBB0_238
	s_cmp_eq_u32 s54, 9
	s_mov_b64 s[10:11], -1
	s_cbranch_scc0 .LBB0_235
	v_pk_add_f32 v[80:81], v[80:81], v[192:193]
	v_pk_add_f32 v[82:83], v[82:83], v[194:195]
	v_pk_add_f32 v[76:77], v[76:77], v[196:197]
	v_pk_add_f32 v[78:79], v[78:79], v[198:199]
	v_mul_f32_e64 v184, |v80|, s23
	v_mul_f32_e64 v185, |v81|, s23
	v_mul_f32_e64 v186, |v82|, s23
	v_mul_f32_e64 v187, |v83|, s23
	v_mul_f32_e64 v188, |v76|, s23
	v_mul_f32_e64 v189, |v77|, s23
	v_mul_f32_e64 v190, |v78|, s23
	v_mul_f32_e64 v191, |v79|, s23
	v_min_f32_e32 v80, 0, v80
	v_min_f32_e32 v81, 0, v81
	v_min_f32_e32 v82, 0, v82
	v_min_f32_e32 v83, 0, v83
	v_min_f32_e32 v76, 0, v76
	v_min_f32_e32 v77, 0, v77
	v_min_f32_e32 v78, 0, v78
	v_min_f32_e32 v79, 0, v79
	v_exp_f32_e32 v184, v184
	v_exp_f32_e32 v185, v185
	v_exp_f32_e32 v186, v186
	v_exp_f32_e32 v187, v187
	v_exp_f32_e32 v188, v188
	v_exp_f32_e32 v189, v189
	v_exp_f32_e32 v190, v190
	v_exp_f32_e32 v191, v191
	v_pk_add_f32 v[184:185], v[184:185], v[228:229]
	v_pk_add_f32 v[186:187], v[186:187], v[228:229]
	v_pk_add_f32 v[188:189], v[188:189], v[228:229]
	v_pk_add_f32 v[190:191], v[190:191], v[228:229]
	v_log_f32_e32 v184, v184
	v_log_f32_e32 v185, v185
	v_log_f32_e32 v186, v186
	v_log_f32_e32 v187, v187
	v_log_f32_e32 v188, v188
	v_log_f32_e32 v189, v189
	v_log_f32_e32 v190, v190
	v_log_f32_e32 v191, v191
	v_pk_mul_f32 v[220:221], v[230:231], v[184:185]
	v_pk_mul_f32 v[222:223], v[230:231], v[186:187]
	v_pk_mul_f32 v[224:225], v[230:231], v[188:189]
	v_pk_mul_f32 v[226:227], v[230:231], v[190:191]
	v_pk_fma_f32 v[220:221], v[184:185], v[230:231], v[220:221] neg_lo:[0,0,1] neg_hi:[0,0,1]
	v_pk_fma_f32 v[222:223], v[186:187], v[230:231], v[222:223] neg_lo:[0,0,1] neg_hi:[0,0,1]
	v_pk_fma_f32 v[224:225], v[188:189], v[230:231], v[224:225] neg_lo:[0,0,1] neg_hi:[0,0,1]
	v_pk_fma_f32 v[226:227], v[190:191], v[230:231], v[226:227] neg_lo:[0,0,1] neg_hi:[0,0,1]
	v_pk_fma_f32 v[220:221], v[232:233], v[184:185], v[220:221]
	v_pk_fma_f32 v[222:223], v[232:233], v[186:187], v[222:223]
	v_pk_fma_f32 v[224:225], v[232:233], v[188:189], v[224:225]
	v_pk_fma_f32 v[226:227], v[232:233], v[190:191], v[226:227]
	v_pk_fma_f32 v[220:221], v[230:231], v[184:185], v[220:221]
	v_pk_fma_f32 v[222:223], v[230:231], v[186:187], v[222:223]
	v_pk_fma_f32 v[224:225], v[230:231], v[188:189], v[224:225]
	v_pk_fma_f32 v[226:227], v[230:231], v[190:191], v[226:227]
	v_pk_add_f32 v[80:81], v[80:81], v[220:221] neg_lo:[0,1] neg_hi:[0,1]
	v_pk_add_f32 v[82:83], v[82:83], v[222:223] neg_lo:[0,1] neg_hi:[0,1]
	v_pk_add_f32 v[76:77], v[76:77], v[224:225] neg_lo:[0,1] neg_hi:[0,1]
	v_pk_add_f32 v[78:79], v[78:79], v[226:227] neg_lo:[0,1] neg_hi:[0,1]
	v_pk_mul_f32 v[80:81], v[234:235], v[80:81]
	v_pk_mul_f32 v[82:83], v[234:235], v[82:83]
	v_pk_mul_f32 v[76:77], v[234:235], v[76:77]
	v_pk_mul_f32 v[78:79], v[234:235], v[78:79]
	v_cvt_pk_bf16_f32 v86, v80, v81
	v_cvt_pk_bf16_f32 v87, v82, v83
	v_cvt_pk_bf16_f32 v88, v76, v77
	v_cvt_pk_bf16_f32 v89, v78, v79
	v_lshl_add_u64 v[84:85], s[16:17], 0, v[92:93]
	v_lshl_add_u64 v[84:85], v[150:151], 1, v[84:85]
	global_store_dwordx4 v[84:85], v[86:89], off sc1
	s_mov_b64 s[10:11], 0

.LBB0_246:
	v_mad_i64_i32 v[76:77], s[34:35], v96, s62, 0
	v_lshl_add_u64 v[76:77], s[14:15], 0, v[76:77]
	s_andn2_b64 vcc, exec, s[10:11]
	v_lshl_add_u64 v[96:97], s[30:31], 1, v[76:77]
	s_cbranch_vccnz .LBB0_248
	v_lshl_add_u64 v[80:81], v[150:151], 1, v[96:97]
	v_cvt_pk_bf16_f32 v76, v84, v85
	v_cvt_pk_bf16_f32 v77, v86, v87
	v_cvt_pk_bf16_f32 v78, v88, v89
	v_cvt_pk_bf16_f32 v79, v90, v91
	global_store_dwordx4 v[80:81], v[76:79], off sc1
.LBB0_248:
	v_mov_b32_e32 v95, v94
	s_nop 0
	v_mov_b32_e32 v76, v94
	v_mov_b32_e32 v77, v94
	v_pk_mul_f32 v[74:75], v[74:75], v[76:77]
	v_pk_mul_f32 v[72:73], v[72:73], v[94:95]
	v_pk_mul_f32 v[70:71], v[70:71], v[76:77]
	v_pk_mul_f32 v[68:69], v[68:69], v[94:95]
	s_mov_b64 s[36:37], -1
	s_mov_b64 s[34:35], 0
	s_cmp_lt_i32 s54, 9
	s_mov_b64 s[10:11], 0
	s_cbranch_scc1 .LBB0_252
	s_cmp_eq_u32 s54, 9
	s_mov_b64 s[10:11], -1
	s_cbranch_scc0 .LBB0_251
	v_pk_add_f32 v[72:73], v[72:73], v[200:201]
	v_pk_add_f32 v[74:75], v[74:75], v[202:203]
	v_pk_add_f32 v[68:69], v[68:69], v[204:205]
	v_pk_add_f32 v[70:71], v[70:71], v[206:207]
	v_mul_f32_e64 v184, |v72|, s23
	v_mul_f32_e64 v185, |v73|, s23
	v_mul_f32_e64 v186, |v74|, s23
	v_mul_f32_e64 v187, |v75|, s23
	v_mul_f32_e64 v188, |v68|, s23
	v_mul_f32_e64 v189, |v69|, s23
	v_mul_f32_e64 v190, |v70|, s23
	v_mul_f32_e64 v191, |v71|, s23
	v_min_f32_e32 v72, 0, v72
	v_min_f32_e32 v73, 0, v73
	v_min_f32_e32 v74, 0, v74
	v_min_f32_e32 v75, 0, v75
	v_min_f32_e32 v68, 0, v68
	v_min_f32_e32 v69, 0, v69
	v_min_f32_e32 v70, 0, v70
	v_min_f32_e32 v71, 0, v71
	v_exp_f32_e32 v184, v184
	v_exp_f32_e32 v185, v185
	v_exp_f32_e32 v186, v186
	v_exp_f32_e32 v187, v187
	v_exp_f32_e32 v188, v188
	v_exp_f32_e32 v189, v189
	v_exp_f32_e32 v190, v190
	v_exp_f32_e32 v191, v191
	v_pk_add_f32 v[184:185], v[184:185], v[228:229]
	v_pk_add_f32 v[186:187], v[186:187], v[228:229]
	v_pk_add_f32 v[188:189], v[188:189], v[228:229]
	v_pk_add_f32 v[190:191], v[190:191], v[228:229]
	v_log_f32_e32 v184, v184
	v_log_f32_e32 v185, v185
	v_log_f32_e32 v186, v186
	v_log_f32_e32 v187, v187
	v_log_f32_e32 v188, v188
	v_log_f32_e32 v189, v189
	v_log_f32_e32 v190, v190
	v_log_f32_e32 v191, v191
	v_pk_mul_f32 v[220:221], v[230:231], v[184:185]
	v_pk_mul_f32 v[222:223], v[230:231], v[186:187]
	v_pk_mul_f32 v[224:225], v[230:231], v[188:189]
	v_pk_mul_f32 v[226:227], v[230:231], v[190:191]
	v_pk_fma_f32 v[220:221], v[184:185], v[230:231], v[220:221] neg_lo:[0,0,1] neg_hi:[0,0,1]
	v_pk_fma_f32 v[222:223], v[186:187], v[230:231], v[222:223] neg_lo:[0,0,1] neg_hi:[0,0,1]
	v_pk_fma_f32 v[224:225], v[188:189], v[230:231], v[224:225] neg_lo:[0,0,1] neg_hi:[0,0,1]
	v_pk_fma_f32 v[226:227], v[190:191], v[230:231], v[226:227] neg_lo:[0,0,1] neg_hi:[0,0,1]
	v_pk_fma_f32 v[220:221], v[232:233], v[184:185], v[220:221]
	v_pk_fma_f32 v[222:223], v[232:233], v[186:187], v[222:223]
	v_pk_fma_f32 v[224:225], v[232:233], v[188:189], v[224:225]
	v_pk_fma_f32 v[226:227], v[232:233], v[190:191], v[226:227]
	v_pk_fma_f32 v[220:221], v[230:231], v[184:185], v[220:221]
	v_pk_fma_f32 v[222:223], v[230:231], v[186:187], v[222:223]
	v_pk_fma_f32 v[224:225], v[230:231], v[188:189], v[224:225]
	v_pk_fma_f32 v[226:227], v[230:231], v[190:191], v[226:227]
	v_pk_add_f32 v[72:73], v[72:73], v[220:221] neg_lo:[0,1] neg_hi:[0,1]
	v_pk_add_f32 v[74:75], v[74:75], v[222:223] neg_lo:[0,1] neg_hi:[0,1]
	v_pk_add_f32 v[68:69], v[68:69], v[224:225] neg_lo:[0,1] neg_hi:[0,1]
	v_pk_add_f32 v[70:71], v[70:71], v[226:227] neg_lo:[0,1] neg_hi:[0,1]
	v_pk_mul_f32 v[72:73], v[234:235], v[72:73]
	v_pk_mul_f32 v[74:75], v[234:235], v[74:75]
	v_pk_mul_f32 v[68:69], v[234:235], v[68:69]
	v_pk_mul_f32 v[70:71], v[234:235], v[70:71]
	v_cvt_pk_bf16_f32 v78, v72, v73
	v_cvt_pk_bf16_f32 v79, v74, v75
	v_cvt_pk_bf16_f32 v80, v68, v69
	v_cvt_pk_bf16_f32 v81, v70, v71
	v_lshl_add_u64 v[76:77], s[16:17], 0, v[92:93]
	v_lshl_add_u64 v[76:77], v[150:151], 1, v[76:77]
	global_store_dwordx4 v[76:77], v[78:81], off offset:256 sc1
	s_mov_b64 s[10:11], 0

.LBB0_259:
	v_lshl_add_u64 v[72:73], v[150:151], 1, v[96:97]
	v_cvt_pk_bf16_f32 v68, v76, v77
	v_cvt_pk_bf16_f32 v69, v78, v79
	v_cvt_pk_bf16_f32 v70, v80, v81
	v_cvt_pk_bf16_f32 v71, v82, v83
	global_store_dwordx4 v[72:73], v[68:71], off offset:256 sc1
.LBB0_260:
	ds_read_b32 v78, v176 offset:512
	v_add_u32_e32 v80, 0x80, v152
	v_ashrrev_i32_e32 v81, 31, v80
	v_lshlrev_b64 v[76:77], 9, v[80:81]
	s_mov_b64 s[36:37], -1
	s_waitcnt lgkmcnt(0)
	v_pk_mul_f32 v[66:67], v[66:67], v[78:79] op_sel_hi:[1,0]
	v_pk_mul_f32 v[64:65], v[64:65], v[78:79] op_sel_hi:[1,0]
	v_pk_mul_f32 v[62:63], v[62:63], v[78:79] op_sel_hi:[1,0]
	v_pk_mul_f32 v[60:61], v[60:61], v[78:79] op_sel_hi:[1,0]
	s_mov_b64 s[34:35], 0
	s_cmp_lt_i32 s54, 9
	s_mov_b64 s[10:11], 0
	s_cbranch_scc1 .LBB0_266
	s_cmp_eq_u32 s54, 9
	s_mov_b64 s[10:11], -1
	s_cbranch_scc0 .LBB0_263
	v_pk_add_f32 v[64:65], v[64:65], v[192:193]
	v_pk_add_f32 v[66:67], v[66:67], v[194:195]
	v_pk_add_f32 v[60:61], v[60:61], v[196:197]
	v_pk_add_f32 v[62:63], v[62:63], v[198:199]
	v_mul_f32_e64 v184, |v64|, s23
	v_mul_f32_e64 v185, |v65|, s23
	v_mul_f32_e64 v186, |v66|, s23
	v_mul_f32_e64 v187, |v67|, s23
	v_mul_f32_e64 v188, |v60|, s23
	v_mul_f32_e64 v189, |v61|, s23
	v_mul_f32_e64 v190, |v62|, s23
	v_mul_f32_e64 v191, |v63|, s23
	v_min_f32_e32 v64, 0, v64
	v_min_f32_e32 v65, 0, v65
	v_min_f32_e32 v66, 0, v66
	v_min_f32_e32 v67, 0, v67
	v_min_f32_e32 v60, 0, v60
	v_min_f32_e32 v61, 0, v61
	v_min_f32_e32 v62, 0, v62
	v_min_f32_e32 v63, 0, v63
	v_exp_f32_e32 v184, v184
	v_exp_f32_e32 v185, v185
	v_exp_f32_e32 v186, v186
	v_exp_f32_e32 v187, v187
	v_exp_f32_e32 v188, v188
	v_exp_f32_e32 v189, v189
	v_exp_f32_e32 v190, v190
	v_exp_f32_e32 v191, v191
	v_pk_add_f32 v[184:185], v[184:185], v[228:229]
	v_pk_add_f32 v[186:187], v[186:187], v[228:229]
	v_pk_add_f32 v[188:189], v[188:189], v[228:229]
	v_pk_add_f32 v[190:191], v[190:191], v[228:229]
	v_log_f32_e32 v184, v184
	v_log_f32_e32 v185, v185
	v_log_f32_e32 v186, v186
	v_log_f32_e32 v187, v187
	v_log_f32_e32 v188, v188
	v_log_f32_e32 v189, v189
	v_log_f32_e32 v190, v190
	v_log_f32_e32 v191, v191
	v_pk_mul_f32 v[220:221], v[230:231], v[184:185]
	v_pk_mul_f32 v[222:223], v[230:231], v[186:187]
	v_pk_mul_f32 v[224:225], v[230:231], v[188:189]
	v_pk_mul_f32 v[226:227], v[230:231], v[190:191]
	v_pk_fma_f32 v[220:221], v[184:185], v[230:231], v[220:221] neg_lo:[0,0,1] neg_hi:[0,0,1]
	v_pk_fma_f32 v[222:223], v[186:187], v[230:231], v[222:223] neg_lo:[0,0,1] neg_hi:[0,0,1]
	v_pk_fma_f32 v[224:225], v[188:189], v[230:231], v[224:225] neg_lo:[0,0,1] neg_hi:[0,0,1]
	v_pk_fma_f32 v[226:227], v[190:191], v[230:231], v[226:227] neg_lo:[0,0,1] neg_hi:[0,0,1]
	v_pk_fma_f32 v[220:221], v[232:233], v[184:185], v[220:221]
	v_pk_fma_f32 v[222:223], v[232:233], v[186:187], v[222:223]
	v_pk_fma_f32 v[224:225], v[232:233], v[188:189], v[224:225]
	v_pk_fma_f32 v[226:227], v[232:233], v[190:191], v[226:227]
	v_pk_fma_f32 v[220:221], v[230:231], v[184:185], v[220:221]
	v_pk_fma_f32 v[222:223], v[230:231], v[186:187], v[222:223]
	v_pk_fma_f32 v[224:225], v[230:231], v[188:189], v[224:225]
	v_pk_fma_f32 v[226:227], v[230:231], v[190:191], v[226:227]
	v_pk_add_f32 v[64:65], v[64:65], v[220:221] neg_lo:[0,1] neg_hi:[0,1]
	v_pk_add_f32 v[66:67], v[66:67], v[222:223] neg_lo:[0,1] neg_hi:[0,1]
	v_pk_add_f32 v[60:61], v[60:61], v[224:225] neg_lo:[0,1] neg_hi:[0,1]
	v_pk_add_f32 v[62:63], v[62:63], v[226:227] neg_lo:[0,1] neg_hi:[0,1]
	v_pk_mul_f32 v[64:65], v[234:235], v[64:65]
	v_pk_mul_f32 v[66:67], v[234:235], v[66:67]
	v_pk_mul_f32 v[60:61], v[234:235], v[60:61]
	v_pk_mul_f32 v[62:63], v[234:235], v[62:63]
	v_cvt_pk_bf16_f32 v70, v64, v65
	v_cvt_pk_bf16_f32 v71, v66, v67
	v_cvt_pk_bf16_f32 v72, v60, v61
	v_cvt_pk_bf16_f32 v73, v62, v63
	v_lshl_add_u64 v[68:69], s[16:17], 0, v[76:77]
	v_lshl_add_u64 v[68:69], v[150:151], 1, v[68:69]
	global_store_dwordx4 v[68:69], v[70:73], off sc1
	s_mov_b64 s[10:11], 0

.LBB0_274:
	v_mad_i64_i32 v[60:61], s[34:35], v80, s62, 0
	v_lshl_add_u64 v[60:61], s[14:15], 0, v[60:61]
	s_andn2_b64 vcc, exec, s[10:11]
	v_lshl_add_u64 v[80:81], s[30:31], 1, v[60:61]
	s_cbranch_vccnz .LBB0_276
	v_lshl_add_u64 v[64:65], v[150:151], 1, v[80:81]
	v_cvt_pk_bf16_f32 v60, v68, v69
	v_cvt_pk_bf16_f32 v61, v70, v71
	v_cvt_pk_bf16_f32 v62, v72, v73
	v_cvt_pk_bf16_f32 v63, v74, v75
	global_store_dwordx4 v[64:65], v[60:63], off sc1
.LBB0_276:
	v_mov_b32_e32 v79, v78
	s_nop 0
	v_mov_b32_e32 v60, v78
	v_mov_b32_e32 v61, v78
	v_pk_mul_f32 v[58:59], v[58:59], v[60:61]
	v_pk_mul_f32 v[56:57], v[56:57], v[78:79]
	v_pk_mul_f32 v[54:55], v[54:55], v[60:61]
	v_pk_mul_f32 v[52:53], v[52:53], v[78:79]
	s_mov_b64 s[36:37], -1
	s_mov_b64 s[34:35], 0
	s_cmp_lt_i32 s54, 9
	s_mov_b64 s[10:11], 0
	s_cbranch_scc1 .LBB0_280
	s_cmp_eq_u32 s54, 9
	s_mov_b64 s[10:11], -1
	s_cbranch_scc0 .LBB0_279
	v_pk_add_f32 v[56:57], v[56:57], v[200:201]
	v_pk_add_f32 v[58:59], v[58:59], v[202:203]
	v_pk_add_f32 v[52:53], v[52:53], v[204:205]
	v_pk_add_f32 v[54:55], v[54:55], v[206:207]
	v_mul_f32_e64 v184, |v56|, s23
	v_mul_f32_e64 v185, |v57|, s23
	v_mul_f32_e64 v186, |v58|, s23
	v_mul_f32_e64 v187, |v59|, s23
	v_mul_f32_e64 v188, |v52|, s23
	v_mul_f32_e64 v189, |v53|, s23
	v_mul_f32_e64 v190, |v54|, s23
	v_mul_f32_e64 v191, |v55|, s23
	v_min_f32_e32 v56, 0, v56
	v_min_f32_e32 v57, 0, v57
	v_min_f32_e32 v58, 0, v58
	v_min_f32_e32 v59, 0, v59
	v_min_f32_e32 v52, 0, v52
	v_min_f32_e32 v53, 0, v53
	v_min_f32_e32 v54, 0, v54
	v_min_f32_e32 v55, 0, v55
	v_exp_f32_e32 v184, v184
	v_exp_f32_e32 v185, v185
	v_exp_f32_e32 v186, v186
	v_exp_f32_e32 v187, v187
	v_exp_f32_e32 v188, v188
	v_exp_f32_e32 v189, v189
	v_exp_f32_e32 v190, v190
	v_exp_f32_e32 v191, v191
	v_pk_add_f32 v[184:185], v[184:185], v[228:229]
	v_pk_add_f32 v[186:187], v[186:187], v[228:229]
	v_pk_add_f32 v[188:189], v[188:189], v[228:229]
	v_pk_add_f32 v[190:191], v[190:191], v[228:229]
	v_log_f32_e32 v184, v184
	v_log_f32_e32 v185, v185
	v_log_f32_e32 v186, v186
	v_log_f32_e32 v187, v187
	v_log_f32_e32 v188, v188
	v_log_f32_e32 v189, v189
	v_log_f32_e32 v190, v190
	v_log_f32_e32 v191, v191
	v_pk_mul_f32 v[220:221], v[230:231], v[184:185]
	v_pk_mul_f32 v[222:223], v[230:231], v[186:187]
	v_pk_mul_f32 v[224:225], v[230:231], v[188:189]
	v_pk_mul_f32 v[226:227], v[230:231], v[190:191]
	v_pk_fma_f32 v[220:221], v[184:185], v[230:231], v[220:221] neg_lo:[0,0,1] neg_hi:[0,0,1]
	v_pk_fma_f32 v[222:223], v[186:187], v[230:231], v[222:223] neg_lo:[0,0,1] neg_hi:[0,0,1]
	v_pk_fma_f32 v[224:225], v[188:189], v[230:231], v[224:225] neg_lo:[0,0,1] neg_hi:[0,0,1]
	v_pk_fma_f32 v[226:227], v[190:191], v[230:231], v[226:227] neg_lo:[0,0,1] neg_hi:[0,0,1]
	v_pk_fma_f32 v[220:221], v[232:233], v[184:185], v[220:221]
	v_pk_fma_f32 v[222:223], v[232:233], v[186:187], v[222:223]
	v_pk_fma_f32 v[224:225], v[232:233], v[188:189], v[224:225]
	v_pk_fma_f32 v[226:227], v[232:233], v[190:191], v[226:227]
	v_pk_fma_f32 v[220:221], v[230:231], v[184:185], v[220:221]
	v_pk_fma_f32 v[222:223], v[230:231], v[186:187], v[222:223]
	v_pk_fma_f32 v[224:225], v[230:231], v[188:189], v[224:225]
	v_pk_fma_f32 v[226:227], v[230:231], v[190:191], v[226:227]
	v_pk_add_f32 v[56:57], v[56:57], v[220:221] neg_lo:[0,1] neg_hi:[0,1]
	v_pk_add_f32 v[58:59], v[58:59], v[222:223] neg_lo:[0,1] neg_hi:[0,1]
	v_pk_add_f32 v[52:53], v[52:53], v[224:225] neg_lo:[0,1] neg_hi:[0,1]
	v_pk_add_f32 v[54:55], v[54:55], v[226:227] neg_lo:[0,1] neg_hi:[0,1]
	v_pk_mul_f32 v[56:57], v[234:235], v[56:57]
	v_pk_mul_f32 v[58:59], v[234:235], v[58:59]
	v_pk_mul_f32 v[52:53], v[234:235], v[52:53]
	v_pk_mul_f32 v[54:55], v[234:235], v[54:55]
	v_cvt_pk_bf16_f32 v62, v56, v57
	v_cvt_pk_bf16_f32 v63, v58, v59
	v_cvt_pk_bf16_f32 v64, v52, v53
	v_cvt_pk_bf16_f32 v65, v54, v55
	v_lshl_add_u64 v[60:61], s[16:17], 0, v[76:77]
	v_lshl_add_u64 v[60:61], v[150:151], 1, v[60:61]
	global_store_dwordx4 v[60:61], v[62:65], off offset:256 sc1
	s_mov_b64 s[10:11], 0

.LBB0_287:
	v_lshl_add_u64 v[56:57], v[150:151], 1, v[80:81]
	v_cvt_pk_bf16_f32 v52, v60, v61
	v_cvt_pk_bf16_f32 v53, v62, v63
	v_cvt_pk_bf16_f32 v54, v64, v65
	v_cvt_pk_bf16_f32 v55, v66, v67
	global_store_dwordx4 v[56:57], v[52:55], off offset:256 sc1
.LBB0_288:
	ds_read_b32 v62, v176 offset:576
	v_add_u32_e32 v64, 0x90, v152
	v_ashrrev_i32_e32 v65, 31, v64
	v_lshlrev_b64 v[60:61], 9, v[64:65]
	s_mov_b64 s[36:37], -1
	s_waitcnt lgkmcnt(0)
	v_pk_mul_f32 v[50:51], v[50:51], v[62:63] op_sel_hi:[1,0]
	v_pk_mul_f32 v[48:49], v[48:49], v[62:63] op_sel_hi:[1,0]
	v_pk_mul_f32 v[46:47], v[46:47], v[62:63] op_sel_hi:[1,0]
	v_pk_mul_f32 v[44:45], v[44:45], v[62:63] op_sel_hi:[1,0]
	s_mov_b64 s[34:35], 0
	s_cmp_lt_i32 s54, 9
	s_mov_b64 s[10:11], 0
	s_cbranch_scc1 .LBB0_294
	s_cmp_eq_u32 s54, 9
	s_mov_b64 s[10:11], -1
	s_cbranch_scc0 .LBB0_291
	v_pk_add_f32 v[48:49], v[48:49], v[192:193]
	v_pk_add_f32 v[50:51], v[50:51], v[194:195]
	v_pk_add_f32 v[44:45], v[44:45], v[196:197]
	v_pk_add_f32 v[46:47], v[46:47], v[198:199]
	v_mul_f32_e64 v184, |v48|, s23
	v_mul_f32_e64 v185, |v49|, s23
	v_mul_f32_e64 v186, |v50|, s23
	v_mul_f32_e64 v187, |v51|, s23
	v_mul_f32_e64 v188, |v44|, s23
	v_mul_f32_e64 v189, |v45|, s23
	v_mul_f32_e64 v190, |v46|, s23
	v_mul_f32_e64 v191, |v47|, s23
	v_min_f32_e32 v48, 0, v48
	v_min_f32_e32 v49, 0, v49
	v_min_f32_e32 v50, 0, v50
	v_min_f32_e32 v51, 0, v51
	v_min_f32_e32 v44, 0, v44
	v_min_f32_e32 v45, 0, v45
	v_min_f32_e32 v46, 0, v46
	v_min_f32_e32 v47, 0, v47
	v_exp_f32_e32 v184, v184
	v_exp_f32_e32 v185, v185
	v_exp_f32_e32 v186, v186
	v_exp_f32_e32 v187, v187
	v_exp_f32_e32 v188, v188
	v_exp_f32_e32 v189, v189
	v_exp_f32_e32 v190, v190
	v_exp_f32_e32 v191, v191
	v_pk_add_f32 v[184:185], v[184:185], v[228:229]
	v_pk_add_f32 v[186:187], v[186:187], v[228:229]
	v_pk_add_f32 v[188:189], v[188:189], v[228:229]
	v_pk_add_f32 v[190:191], v[190:191], v[228:229]
	v_log_f32_e32 v184, v184
	v_log_f32_e32 v185, v185
	v_log_f32_e32 v186, v186
	v_log_f32_e32 v187, v187
	v_log_f32_e32 v188, v188
	v_log_f32_e32 v189, v189
	v_log_f32_e32 v190, v190
	v_log_f32_e32 v191, v191
	v_pk_mul_f32 v[220:221], v[230:231], v[184:185]
	v_pk_mul_f32 v[222:223], v[230:231], v[186:187]
	v_pk_mul_f32 v[224:225], v[230:231], v[188:189]
	v_pk_mul_f32 v[226:227], v[230:231], v[190:191]
	v_pk_fma_f32 v[220:221], v[184:185], v[230:231], v[220:221] neg_lo:[0,0,1] neg_hi:[0,0,1]
	v_pk_fma_f32 v[222:223], v[186:187], v[230:231], v[222:223] neg_lo:[0,0,1] neg_hi:[0,0,1]
	v_pk_fma_f32 v[224:225], v[188:189], v[230:231], v[224:225] neg_lo:[0,0,1] neg_hi:[0,0,1]
	v_pk_fma_f32 v[226:227], v[190:191], v[230:231], v[226:227] neg_lo:[0,0,1] neg_hi:[0,0,1]
	v_pk_fma_f32 v[220:221], v[232:233], v[184:185], v[220:221]
	v_pk_fma_f32 v[222:223], v[232:233], v[186:187], v[222:223]
	v_pk_fma_f32 v[224:225], v[232:233], v[188:189], v[224:225]
	v_pk_fma_f32 v[226:227], v[232:233], v[190:191], v[226:227]
	v_pk_fma_f32 v[220:221], v[230:231], v[184:185], v[220:221]
	v_pk_fma_f32 v[222:223], v[230:231], v[186:187], v[222:223]
	v_pk_fma_f32 v[224:225], v[230:231], v[188:189], v[224:225]
	v_pk_fma_f32 v[226:227], v[230:231], v[190:191], v[226:227]
	v_pk_add_f32 v[48:49], v[48:49], v[220:221] neg_lo:[0,1] neg_hi:[0,1]
	v_pk_add_f32 v[50:51], v[50:51], v[222:223] neg_lo:[0,1] neg_hi:[0,1]
	v_pk_add_f32 v[44:45], v[44:45], v[224:225] neg_lo:[0,1] neg_hi:[0,1]
	v_pk_add_f32 v[46:47], v[46:47], v[226:227] neg_lo:[0,1] neg_hi:[0,1]
	v_pk_mul_f32 v[48:49], v[234:235], v[48:49]
	v_pk_mul_f32 v[50:51], v[234:235], v[50:51]
	v_pk_mul_f32 v[44:45], v[234:235], v[44:45]
	v_pk_mul_f32 v[46:47], v[234:235], v[46:47]
	v_cvt_pk_bf16_f32 v54, v48, v49
	v_cvt_pk_bf16_f32 v55, v50, v51
	v_cvt_pk_bf16_f32 v56, v44, v45
	v_cvt_pk_bf16_f32 v57, v46, v47
	v_lshl_add_u64 v[52:53], s[16:17], 0, v[60:61]
	v_lshl_add_u64 v[52:53], v[150:151], 1, v[52:53]
	global_store_dwordx4 v[52:53], v[54:57], off sc1
	s_mov_b64 s[10:11], 0

.LBB0_302:
	v_mad_i64_i32 v[44:45], s[34:35], v64, s62, 0
	v_lshl_add_u64 v[44:45], s[14:15], 0, v[44:45]
	s_andn2_b64 vcc, exec, s[10:11]
	v_lshl_add_u64 v[64:65], s[30:31], 1, v[44:45]
	s_cbranch_vccnz .LBB0_304
	v_lshl_add_u64 v[48:49], v[150:151], 1, v[64:65]
	v_cvt_pk_bf16_f32 v44, v52, v53
	v_cvt_pk_bf16_f32 v45, v54, v55
	v_cvt_pk_bf16_f32 v46, v56, v57
	v_cvt_pk_bf16_f32 v47, v58, v59
	global_store_dwordx4 v[48:49], v[44:47], off sc1
.LBB0_304:
	v_mov_b32_e32 v63, v62
	s_nop 0
	v_mov_b32_e32 v44, v62
	v_mov_b32_e32 v45, v62
	v_pk_mul_f32 v[42:43], v[42:43], v[44:45]
	v_pk_mul_f32 v[40:41], v[40:41], v[62:63]
	v_pk_mul_f32 v[38:39], v[38:39], v[44:45]
	v_pk_mul_f32 v[36:37], v[36:37], v[62:63]
	s_mov_b64 s[36:37], -1
	s_mov_b64 s[34:35], 0
	s_cmp_lt_i32 s54, 9
	s_mov_b64 s[10:11], 0
	s_cbranch_scc1 .LBB0_308
	s_cmp_eq_u32 s54, 9
	s_mov_b64 s[10:11], -1
	s_cbranch_scc0 .LBB0_307
	v_pk_add_f32 v[40:41], v[40:41], v[200:201]
	v_pk_add_f32 v[42:43], v[42:43], v[202:203]
	v_pk_add_f32 v[36:37], v[36:37], v[204:205]
	v_pk_add_f32 v[38:39], v[38:39], v[206:207]
	v_mul_f32_e64 v184, |v40|, s23
	v_mul_f32_e64 v185, |v41|, s23
	v_mul_f32_e64 v186, |v42|, s23
	v_mul_f32_e64 v187, |v43|, s23
	v_mul_f32_e64 v188, |v36|, s23
	v_mul_f32_e64 v189, |v37|, s23
	v_mul_f32_e64 v190, |v38|, s23
	v_mul_f32_e64 v191, |v39|, s23
	v_min_f32_e32 v40, 0, v40
	v_min_f32_e32 v41, 0, v41
	v_min_f32_e32 v42, 0, v42
	v_min_f32_e32 v43, 0, v43
	v_min_f32_e32 v36, 0, v36
	v_min_f32_e32 v37, 0, v37
	v_min_f32_e32 v38, 0, v38
	v_min_f32_e32 v39, 0, v39
	v_exp_f32_e32 v184, v184
	v_exp_f32_e32 v185, v185
	v_exp_f32_e32 v186, v186
	v_exp_f32_e32 v187, v187
	v_exp_f32_e32 v188, v188
	v_exp_f32_e32 v189, v189
	v_exp_f32_e32 v190, v190
	v_exp_f32_e32 v191, v191
	v_pk_add_f32 v[184:185], v[184:185], v[228:229]
	v_pk_add_f32 v[186:187], v[186:187], v[228:229]
	v_pk_add_f32 v[188:189], v[188:189], v[228:229]
	v_pk_add_f32 v[190:191], v[190:191], v[228:229]
	v_log_f32_e32 v184, v184
	v_log_f32_e32 v185, v185
	v_log_f32_e32 v186, v186
	v_log_f32_e32 v187, v187
	v_log_f32_e32 v188, v188
	v_log_f32_e32 v189, v189
	v_log_f32_e32 v190, v190
	v_log_f32_e32 v191, v191
	v_pk_mul_f32 v[220:221], v[230:231], v[184:185]
	v_pk_mul_f32 v[222:223], v[230:231], v[186:187]
	v_pk_mul_f32 v[224:225], v[230:231], v[188:189]
	v_pk_mul_f32 v[226:227], v[230:231], v[190:191]
	v_pk_fma_f32 v[220:221], v[184:185], v[230:231], v[220:221] neg_lo:[0,0,1] neg_hi:[0,0,1]
	v_pk_fma_f32 v[222:223], v[186:187], v[230:231], v[222:223] neg_lo:[0,0,1] neg_hi:[0,0,1]
	v_pk_fma_f32 v[224:225], v[188:189], v[230:231], v[224:225] neg_lo:[0,0,1] neg_hi:[0,0,1]
	v_pk_fma_f32 v[226:227], v[190:191], v[230:231], v[226:227] neg_lo:[0,0,1] neg_hi:[0,0,1]
	v_pk_fma_f32 v[220:221], v[232:233], v[184:185], v[220:221]
	v_pk_fma_f32 v[222:223], v[232:233], v[186:187], v[222:223]
	v_pk_fma_f32 v[224:225], v[232:233], v[188:189], v[224:225]
	v_pk_fma_f32 v[226:227], v[232:233], v[190:191], v[226:227]
	v_pk_fma_f32 v[220:221], v[230:231], v[184:185], v[220:221]
	v_pk_fma_f32 v[222:223], v[230:231], v[186:187], v[222:223]
	v_pk_fma_f32 v[224:225], v[230:231], v[188:189], v[224:225]
	v_pk_fma_f32 v[226:227], v[230:231], v[190:191], v[226:227]
	v_pk_add_f32 v[40:41], v[40:41], v[220:221] neg_lo:[0,1] neg_hi:[0,1]
	v_pk_add_f32 v[42:43], v[42:43], v[222:223] neg_lo:[0,1] neg_hi:[0,1]
	v_pk_add_f32 v[36:37], v[36:37], v[224:225] neg_lo:[0,1] neg_hi:[0,1]
	v_pk_add_f32 v[38:39], v[38:39], v[226:227] neg_lo:[0,1] neg_hi:[0,1]
	v_pk_mul_f32 v[40:41], v[234:235], v[40:41]
	v_pk_mul_f32 v[42:43], v[234:235], v[42:43]
	v_pk_mul_f32 v[36:37], v[234:235], v[36:37]
	v_pk_mul_f32 v[38:39], v[234:235], v[38:39]
	v_cvt_pk_bf16_f32 v46, v40, v41
	v_cvt_pk_bf16_f32 v47, v42, v43
	v_cvt_pk_bf16_f32 v48, v36, v37
	v_cvt_pk_bf16_f32 v49, v38, v39
	v_lshl_add_u64 v[44:45], s[16:17], 0, v[60:61]
	v_lshl_add_u64 v[44:45], v[150:151], 1, v[44:45]
	global_store_dwordx4 v[44:45], v[46:49], off offset:256 sc1
	s_mov_b64 s[10:11], 0

.LBB0_315:
	v_lshl_add_u64 v[40:41], v[150:151], 1, v[64:65]
	v_cvt_pk_bf16_f32 v36, v44, v45
	v_cvt_pk_bf16_f32 v37, v46, v47
	v_cvt_pk_bf16_f32 v38, v48, v49
	v_cvt_pk_bf16_f32 v39, v50, v51
	global_store_dwordx4 v[40:41], v[36:39], off offset:256 sc1
.LBB0_316:
	ds_read_b32 v46, v176 offset:640
	v_add_u32_e32 v48, 0xa0, v152
	v_ashrrev_i32_e32 v49, 31, v48
	v_lshlrev_b64 v[44:45], 9, v[48:49]
	s_mov_b64 s[36:37], -1
	s_waitcnt lgkmcnt(0)
	v_pk_mul_f32 v[34:35], v[34:35], v[46:47] op_sel_hi:[1,0]
	v_pk_mul_f32 v[32:33], v[32:33], v[46:47] op_sel_hi:[1,0]
	v_pk_mul_f32 v[30:31], v[30:31], v[46:47] op_sel_hi:[1,0]
	v_pk_mul_f32 v[28:29], v[28:29], v[46:47] op_sel_hi:[1,0]
	s_mov_b64 s[34:35], 0
	s_cmp_lt_i32 s54, 9
	s_mov_b64 s[10:11], 0
	s_cbranch_scc1 .LBB0_322
	s_cmp_eq_u32 s54, 9
	s_mov_b64 s[10:11], -1
	s_cbranch_scc0 .LBB0_319
	v_pk_add_f32 v[32:33], v[32:33], v[192:193]
	v_pk_add_f32 v[34:35], v[34:35], v[194:195]
	v_pk_add_f32 v[28:29], v[28:29], v[196:197]
	v_pk_add_f32 v[30:31], v[30:31], v[198:199]
	v_mul_f32_e64 v184, |v32|, s23
	v_mul_f32_e64 v185, |v33|, s23
	v_mul_f32_e64 v186, |v34|, s23
	v_mul_f32_e64 v187, |v35|, s23
	v_mul_f32_e64 v188, |v28|, s23
	v_mul_f32_e64 v189, |v29|, s23
	v_mul_f32_e64 v190, |v30|, s23
	v_mul_f32_e64 v191, |v31|, s23
	v_min_f32_e32 v32, 0, v32
	v_min_f32_e32 v33, 0, v33
	v_min_f32_e32 v34, 0, v34
	v_min_f32_e32 v35, 0, v35
	v_min_f32_e32 v28, 0, v28
	v_min_f32_e32 v29, 0, v29
	v_min_f32_e32 v30, 0, v30
	v_min_f32_e32 v31, 0, v31
	v_exp_f32_e32 v184, v184
	v_exp_f32_e32 v185, v185
	v_exp_f32_e32 v186, v186
	v_exp_f32_e32 v187, v187
	v_exp_f32_e32 v188, v188
	v_exp_f32_e32 v189, v189
	v_exp_f32_e32 v190, v190
	v_exp_f32_e32 v191, v191
	v_pk_add_f32 v[184:185], v[184:185], v[228:229]
	v_pk_add_f32 v[186:187], v[186:187], v[228:229]
	v_pk_add_f32 v[188:189], v[188:189], v[228:229]
	v_pk_add_f32 v[190:191], v[190:191], v[228:229]
	v_log_f32_e32 v184, v184
	v_log_f32_e32 v185, v185
	v_log_f32_e32 v186, v186
	v_log_f32_e32 v187, v187
	v_log_f32_e32 v188, v188
	v_log_f32_e32 v189, v189
	v_log_f32_e32 v190, v190
	v_log_f32_e32 v191, v191
	v_pk_mul_f32 v[220:221], v[230:231], v[184:185]
	v_pk_mul_f32 v[222:223], v[230:231], v[186:187]
	v_pk_mul_f32 v[224:225], v[230:231], v[188:189]
	v_pk_mul_f32 v[226:227], v[230:231], v[190:191]
	v_pk_fma_f32 v[220:221], v[184:185], v[230:231], v[220:221] neg_lo:[0,0,1] neg_hi:[0,0,1]
	v_pk_fma_f32 v[222:223], v[186:187], v[230:231], v[222:223] neg_lo:[0,0,1] neg_hi:[0,0,1]
	v_pk_fma_f32 v[224:225], v[188:189], v[230:231], v[224:225] neg_lo:[0,0,1] neg_hi:[0,0,1]
	v_pk_fma_f32 v[226:227], v[190:191], v[230:231], v[226:227] neg_lo:[0,0,1] neg_hi:[0,0,1]
	v_pk_fma_f32 v[220:221], v[232:233], v[184:185], v[220:221]
	v_pk_fma_f32 v[222:223], v[232:233], v[186:187], v[222:223]
	v_pk_fma_f32 v[224:225], v[232:233], v[188:189], v[224:225]
	v_pk_fma_f32 v[226:227], v[232:233], v[190:191], v[226:227]
	v_pk_fma_f32 v[220:221], v[230:231], v[184:185], v[220:221]
	v_pk_fma_f32 v[222:223], v[230:231], v[186:187], v[222:223]
	v_pk_fma_f32 v[224:225], v[230:231], v[188:189], v[224:225]
	v_pk_fma_f32 v[226:227], v[230:231], v[190:191], v[226:227]
	v_pk_add_f32 v[32:33], v[32:33], v[220:221] neg_lo:[0,1] neg_hi:[0,1]
	v_pk_add_f32 v[34:35], v[34:35], v[222:223] neg_lo:[0,1] neg_hi:[0,1]
	v_pk_add_f32 v[28:29], v[28:29], v[224:225] neg_lo:[0,1] neg_hi:[0,1]
	v_pk_add_f32 v[30:31], v[30:31], v[226:227] neg_lo:[0,1] neg_hi:[0,1]
	v_pk_mul_f32 v[32:33], v[234:235], v[32:33]
	v_pk_mul_f32 v[34:35], v[234:235], v[34:35]
	v_pk_mul_f32 v[28:29], v[234:235], v[28:29]
	v_pk_mul_f32 v[30:31], v[234:235], v[30:31]
	v_cvt_pk_bf16_f32 v38, v32, v33
	v_cvt_pk_bf16_f32 v39, v34, v35
	v_cvt_pk_bf16_f32 v40, v28, v29
	v_cvt_pk_bf16_f32 v41, v30, v31
	v_lshl_add_u64 v[36:37], s[16:17], 0, v[44:45]
	v_lshl_add_u64 v[36:37], v[150:151], 1, v[36:37]
	global_store_dwordx4 v[36:37], v[38:41], off sc1
	s_mov_b64 s[10:11], 0

.LBB0_330:
	v_mad_i64_i32 v[28:29], s[34:35], v48, s62, 0
	v_lshl_add_u64 v[28:29], s[14:15], 0, v[28:29]
	s_andn2_b64 vcc, exec, s[10:11]
	v_lshl_add_u64 v[48:49], s[30:31], 1, v[28:29]
	s_cbranch_vccnz .LBB0_332
	v_lshl_add_u64 v[32:33], v[150:151], 1, v[48:49]
	v_cvt_pk_bf16_f32 v28, v36, v37
	v_cvt_pk_bf16_f32 v29, v38, v39
	v_cvt_pk_bf16_f32 v30, v40, v41
	v_cvt_pk_bf16_f32 v31, v42, v43
	global_store_dwordx4 v[32:33], v[28:31], off sc1
.LBB0_332:
	v_mov_b32_e32 v47, v46
	s_nop 0
	v_mov_b32_e32 v28, v46
	v_mov_b32_e32 v29, v46
	v_pk_mul_f32 v[26:27], v[26:27], v[28:29]
	v_pk_mul_f32 v[24:25], v[24:25], v[46:47]
	v_pk_mul_f32 v[22:23], v[22:23], v[28:29]
	v_pk_mul_f32 v[20:21], v[20:21], v[46:47]
	s_mov_b64 s[36:37], -1
	s_mov_b64 s[34:35], 0
	s_cmp_lt_i32 s54, 9
	s_mov_b64 s[10:11], 0
	s_cbranch_scc1 .LBB0_336
	s_cmp_eq_u32 s54, 9
	s_mov_b64 s[10:11], -1
	s_cbranch_scc0 .LBB0_335
	v_pk_add_f32 v[24:25], v[24:25], v[200:201]
	v_pk_add_f32 v[26:27], v[26:27], v[202:203]
	v_pk_add_f32 v[20:21], v[20:21], v[204:205]
	v_pk_add_f32 v[22:23], v[22:23], v[206:207]
	v_mul_f32_e64 v184, |v24|, s23
	v_mul_f32_e64 v185, |v25|, s23
	v_mul_f32_e64 v186, |v26|, s23
	v_mul_f32_e64 v187, |v27|, s23
	v_mul_f32_e64 v188, |v20|, s23
	v_mul_f32_e64 v189, |v21|, s23
	v_mul_f32_e64 v190, |v22|, s23
	v_mul_f32_e64 v191, |v23|, s23
	v_min_f32_e32 v24, 0, v24
	v_min_f32_e32 v25, 0, v25
	v_min_f32_e32 v26, 0, v26
	v_min_f32_e32 v27, 0, v27
	v_min_f32_e32 v20, 0, v20
	v_min_f32_e32 v21, 0, v21
	v_min_f32_e32 v22, 0, v22
	v_min_f32_e32 v23, 0, v23
	v_exp_f32_e32 v184, v184
	v_exp_f32_e32 v185, v185
	v_exp_f32_e32 v186, v186
	v_exp_f32_e32 v187, v187
	v_exp_f32_e32 v188, v188
	v_exp_f32_e32 v189, v189
	v_exp_f32_e32 v190, v190
	v_exp_f32_e32 v191, v191
	v_pk_add_f32 v[184:185], v[184:185], v[228:229]
	v_pk_add_f32 v[186:187], v[186:187], v[228:229]
	v_pk_add_f32 v[188:189], v[188:189], v[228:229]
	v_pk_add_f32 v[190:191], v[190:191], v[228:229]
	v_log_f32_e32 v184, v184
	v_log_f32_e32 v185, v185
	v_log_f32_e32 v186, v186
	v_log_f32_e32 v187, v187
	v_log_f32_e32 v188, v188
	v_log_f32_e32 v189, v189
	v_log_f32_e32 v190, v190
	v_log_f32_e32 v191, v191
	v_pk_mul_f32 v[220:221], v[230:231], v[184:185]
	v_pk_mul_f32 v[222:223], v[230:231], v[186:187]
	v_pk_mul_f32 v[224:225], v[230:231], v[188:189]
	v_pk_mul_f32 v[226:227], v[230:231], v[190:191]
	v_pk_fma_f32 v[220:221], v[184:185], v[230:231], v[220:221] neg_lo:[0,0,1] neg_hi:[0,0,1]
	v_pk_fma_f32 v[222:223], v[186:187], v[230:231], v[222:223] neg_lo:[0,0,1] neg_hi:[0,0,1]
	v_pk_fma_f32 v[224:225], v[188:189], v[230:231], v[224:225] neg_lo:[0,0,1] neg_hi:[0,0,1]
	v_pk_fma_f32 v[226:227], v[190:191], v[230:231], v[226:227] neg_lo:[0,0,1] neg_hi:[0,0,1]
	v_pk_fma_f32 v[220:221], v[232:233], v[184:185], v[220:221]
	v_pk_fma_f32 v[222:223], v[232:233], v[186:187], v[222:223]
	v_pk_fma_f32 v[224:225], v[232:233], v[188:189], v[224:225]
	v_pk_fma_f32 v[226:227], v[232:233], v[190:191], v[226:227]
	v_pk_fma_f32 v[220:221], v[230:231], v[184:185], v[220:221]
	v_pk_fma_f32 v[222:223], v[230:231], v[186:187], v[222:223]
	v_pk_fma_f32 v[224:225], v[230:231], v[188:189], v[224:225]
	v_pk_fma_f32 v[226:227], v[230:231], v[190:191], v[226:227]
	v_pk_add_f32 v[24:25], v[24:25], v[220:221] neg_lo:[0,1] neg_hi:[0,1]
	v_pk_add_f32 v[26:27], v[26:27], v[222:223] neg_lo:[0,1] neg_hi:[0,1]
	v_pk_add_f32 v[20:21], v[20:21], v[224:225] neg_lo:[0,1] neg_hi:[0,1]
	v_pk_add_f32 v[22:23], v[22:23], v[226:227] neg_lo:[0,1] neg_hi:[0,1]
	v_pk_mul_f32 v[24:25], v[234:235], v[24:25]
	v_pk_mul_f32 v[26:27], v[234:235], v[26:27]
	v_pk_mul_f32 v[20:21], v[234:235], v[20:21]
	v_pk_mul_f32 v[22:23], v[234:235], v[22:23]
	v_cvt_pk_bf16_f32 v30, v24, v25
	v_cvt_pk_bf16_f32 v31, v26, v27
	v_cvt_pk_bf16_f32 v32, v20, v21
	v_cvt_pk_bf16_f32 v33, v22, v23
	v_lshl_add_u64 v[28:29], s[16:17], 0, v[44:45]
	v_lshl_add_u64 v[28:29], v[150:151], 1, v[28:29]
	global_store_dwordx4 v[28:29], v[30:33], off offset:256 sc1
	s_mov_b64 s[10:11], 0

.LBB0_343:
	v_lshl_add_u64 v[24:25], v[150:151], 1, v[48:49]
	v_cvt_pk_bf16_f32 v20, v28, v29
	v_cvt_pk_bf16_f32 v21, v30, v31
	v_cvt_pk_bf16_f32 v22, v32, v33
	v_cvt_pk_bf16_f32 v23, v34, v35
	global_store_dwordx4 v[24:25], v[20:23], off offset:256 sc1
.LBB0_344:
	ds_read_b32 v30, v176 offset:704
	v_add_u32_e32 v32, 0xb0, v152
	v_ashrrev_i32_e32 v33, 31, v32
	v_lshlrev_b64 v[28:29], 9, v[32:33]
	s_mov_b64 s[36:37], -1
	s_waitcnt lgkmcnt(0)
	v_pk_mul_f32 v[18:19], v[18:19], v[30:31] op_sel_hi:[1,0]
	v_pk_mul_f32 v[16:17], v[16:17], v[30:31] op_sel_hi:[1,0]
	v_pk_mul_f32 v[14:15], v[14:15], v[30:31] op_sel_hi:[1,0]
	v_pk_mul_f32 v[12:13], v[12:13], v[30:31] op_sel_hi:[1,0]
	s_mov_b64 s[34:35], 0
	s_cmp_lt_i32 s54, 9
	s_mov_b64 s[10:11], 0
	s_cbranch_scc1 .LBB0_350
	s_cmp_eq_u32 s54, 9
	s_mov_b64 s[10:11], -1
	s_cbranch_scc0 .LBB0_347
	v_pk_add_f32 v[16:17], v[16:17], v[192:193]
	v_pk_add_f32 v[18:19], v[18:19], v[194:195]
	v_pk_add_f32 v[12:13], v[12:13], v[196:197]
	v_pk_add_f32 v[14:15], v[14:15], v[198:199]
	v_mul_f32_e64 v184, |v16|, s23
	v_mul_f32_e64 v185, |v17|, s23
	v_mul_f32_e64 v186, |v18|, s23
	v_mul_f32_e64 v187, |v19|, s23
	v_mul_f32_e64 v188, |v12|, s23
	v_mul_f32_e64 v189, |v13|, s23
	v_mul_f32_e64 v190, |v14|, s23
	v_mul_f32_e64 v191, |v15|, s23
	v_min_f32_e32 v16, 0, v16
	v_min_f32_e32 v17, 0, v17
	v_min_f32_e32 v18, 0, v18
	v_min_f32_e32 v19, 0, v19
	v_min_f32_e32 v12, 0, v12
	v_min_f32_e32 v13, 0, v13
	v_min_f32_e32 v14, 0, v14
	v_min_f32_e32 v15, 0, v15
	v_exp_f32_e32 v184, v184
	v_exp_f32_e32 v185, v185
	v_exp_f32_e32 v186, v186
	v_exp_f32_e32 v187, v187
	v_exp_f32_e32 v188, v188
	v_exp_f32_e32 v189, v189
	v_exp_f32_e32 v190, v190
	v_exp_f32_e32 v191, v191
	v_pk_add_f32 v[184:185], v[184:185], v[228:229]
	v_pk_add_f32 v[186:187], v[186:187], v[228:229]
	v_pk_add_f32 v[188:189], v[188:189], v[228:229]
	v_pk_add_f32 v[190:191], v[190:191], v[228:229]
	v_log_f32_e32 v184, v184
	v_log_f32_e32 v185, v185
	v_log_f32_e32 v186, v186
	v_log_f32_e32 v187, v187
	v_log_f32_e32 v188, v188
	v_log_f32_e32 v189, v189
	v_log_f32_e32 v190, v190
	v_log_f32_e32 v191, v191
	v_pk_mul_f32 v[220:221], v[230:231], v[184:185]
	v_pk_mul_f32 v[222:223], v[230:231], v[186:187]
	v_pk_mul_f32 v[224:225], v[230:231], v[188:189]
	v_pk_mul_f32 v[226:227], v[230:231], v[190:191]
	v_pk_fma_f32 v[220:221], v[184:185], v[230:231], v[220:221] neg_lo:[0,0,1] neg_hi:[0,0,1]
	v_pk_fma_f32 v[222:223], v[186:187], v[230:231], v[222:223] neg_lo:[0,0,1] neg_hi:[0,0,1]
	v_pk_fma_f32 v[224:225], v[188:189], v[230:231], v[224:225] neg_lo:[0,0,1] neg_hi:[0,0,1]
	v_pk_fma_f32 v[226:227], v[190:191], v[230:231], v[226:227] neg_lo:[0,0,1] neg_hi:[0,0,1]
	v_pk_fma_f32 v[220:221], v[232:233], v[184:185], v[220:221]
	v_pk_fma_f32 v[222:223], v[232:233], v[186:187], v[222:223]
	v_pk_fma_f32 v[224:225], v[232:233], v[188:189], v[224:225]
	v_pk_fma_f32 v[226:227], v[232:233], v[190:191], v[226:227]
	v_pk_fma_f32 v[220:221], v[230:231], v[184:185], v[220:221]
	v_pk_fma_f32 v[222:223], v[230:231], v[186:187], v[222:223]
	v_pk_fma_f32 v[224:225], v[230:231], v[188:189], v[224:225]
	v_pk_fma_f32 v[226:227], v[230:231], v[190:191], v[226:227]
	v_pk_add_f32 v[16:17], v[16:17], v[220:221] neg_lo:[0,1] neg_hi:[0,1]
	v_pk_add_f32 v[18:19], v[18:19], v[222:223] neg_lo:[0,1] neg_hi:[0,1]
	v_pk_add_f32 v[12:13], v[12:13], v[224:225] neg_lo:[0,1] neg_hi:[0,1]
	v_pk_add_f32 v[14:15], v[14:15], v[226:227] neg_lo:[0,1] neg_hi:[0,1]
	v_pk_mul_f32 v[16:17], v[234:235], v[16:17]
	v_pk_mul_f32 v[18:19], v[234:235], v[18:19]
	v_pk_mul_f32 v[12:13], v[234:235], v[12:13]
	v_pk_mul_f32 v[14:15], v[234:235], v[14:15]
	v_cvt_pk_bf16_f32 v22, v16, v17
	v_cvt_pk_bf16_f32 v23, v18, v19
	v_cvt_pk_bf16_f32 v24, v12, v13
	v_cvt_pk_bf16_f32 v25, v14, v15
	v_lshl_add_u64 v[20:21], s[16:17], 0, v[28:29]
	v_lshl_add_u64 v[20:21], v[150:151], 1, v[20:21]
	global_store_dwordx4 v[20:21], v[22:25], off sc1
	s_mov_b64 s[10:11], 0

.LBB0_358:
	v_mad_i64_i32 v[12:13], s[34:35], v32, s62, 0
	v_lshl_add_u64 v[12:13], s[14:15], 0, v[12:13]
	s_andn2_b64 vcc, exec, s[10:11]
	v_lshl_add_u64 v[32:33], s[30:31], 1, v[12:13]
	s_cbranch_vccnz .LBB0_360
	v_lshl_add_u64 v[16:17], v[150:151], 1, v[32:33]
	v_cvt_pk_bf16_f32 v12, v20, v21
	v_cvt_pk_bf16_f32 v13, v22, v23
	v_cvt_pk_bf16_f32 v14, v24, v25
	v_cvt_pk_bf16_f32 v15, v26, v27
	global_store_dwordx4 v[16:17], v[12:15], off sc1
.LBB0_360:
	v_mov_b32_e32 v31, v30
	s_nop 0
	v_mov_b32_e32 v12, v30
	v_mov_b32_e32 v13, v30
	v_pk_mul_f32 v[10:11], v[10:11], v[12:13]
	v_pk_mul_f32 v[8:9], v[8:9], v[30:31]
	v_pk_mul_f32 v[6:7], v[6:7], v[12:13]
	v_pk_mul_f32 v[4:5], v[4:5], v[30:31]
	s_mov_b64 s[34:35], -1
	s_mov_b64 s[30:31], 0
	s_cmp_lt_i32 s54, 9
	s_mov_b64 s[10:11], 0
	s_cbranch_scc1 .LBB0_364
	s_cmp_eq_u32 s54, 9
	s_mov_b64 s[10:11], -1
	s_cbranch_scc0 .LBB0_363
	v_pk_add_f32 v[8:9], v[8:9], v[200:201]
	v_pk_add_f32 v[10:11], v[10:11], v[202:203]
	v_pk_add_f32 v[4:5], v[4:5], v[204:205]
	v_pk_add_f32 v[6:7], v[6:7], v[206:207]
	v_mul_f32_e64 v184, |v8|, s23
	v_mul_f32_e64 v185, |v9|, s23
	v_mul_f32_e64 v186, |v10|, s23
	v_mul_f32_e64 v187, |v11|, s23
	v_mul_f32_e64 v188, |v4|, s23
	v_mul_f32_e64 v189, |v5|, s23
	v_mul_f32_e64 v190, |v6|, s23
	v_mul_f32_e64 v191, |v7|, s23
	v_min_f32_e32 v8, 0, v8
	v_min_f32_e32 v9, 0, v9
	v_min_f32_e32 v10, 0, v10
	v_min_f32_e32 v11, 0, v11
	v_min_f32_e32 v4, 0, v4
	v_min_f32_e32 v5, 0, v5
	v_min_f32_e32 v6, 0, v6
	v_min_f32_e32 v7, 0, v7
	v_exp_f32_e32 v184, v184
	v_exp_f32_e32 v185, v185
	v_exp_f32_e32 v186, v186
	v_exp_f32_e32 v187, v187
	v_exp_f32_e32 v188, v188
	v_exp_f32_e32 v189, v189
	v_exp_f32_e32 v190, v190
	v_exp_f32_e32 v191, v191
	v_pk_add_f32 v[184:185], v[184:185], v[228:229]
	v_pk_add_f32 v[186:187], v[186:187], v[228:229]
	v_pk_add_f32 v[188:189], v[188:189], v[228:229]
	v_pk_add_f32 v[190:191], v[190:191], v[228:229]
	v_log_f32_e32 v184, v184
	v_log_f32_e32 v185, v185
	v_log_f32_e32 v186, v186
	v_log_f32_e32 v187, v187
	v_log_f32_e32 v188, v188
	v_log_f32_e32 v189, v189
	v_log_f32_e32 v190, v190
	v_log_f32_e32 v191, v191
	v_pk_mul_f32 v[220:221], v[230:231], v[184:185]
	v_pk_mul_f32 v[222:223], v[230:231], v[186:187]
	v_pk_mul_f32 v[224:225], v[230:231], v[188:189]
	v_pk_mul_f32 v[226:227], v[230:231], v[190:191]
	v_pk_fma_f32 v[220:221], v[184:185], v[230:231], v[220:221] neg_lo:[0,0,1] neg_hi:[0,0,1]
	v_pk_fma_f32 v[222:223], v[186:187], v[230:231], v[222:223] neg_lo:[0,0,1] neg_hi:[0,0,1]
	v_pk_fma_f32 v[224:225], v[188:189], v[230:231], v[224:225] neg_lo:[0,0,1] neg_hi:[0,0,1]
	v_pk_fma_f32 v[226:227], v[190:191], v[230:231], v[226:227] neg_lo:[0,0,1] neg_hi:[0,0,1]
	v_pk_fma_f32 v[220:221], v[232:233], v[184:185], v[220:221]
	v_pk_fma_f32 v[222:223], v[232:233], v[186:187], v[222:223]
	v_pk_fma_f32 v[224:225], v[232:233], v[188:189], v[224:225]
	v_pk_fma_f32 v[226:227], v[232:233], v[190:191], v[226:227]
	v_pk_fma_f32 v[220:221], v[230:231], v[184:185], v[220:221]
	v_pk_fma_f32 v[222:223], v[230:231], v[186:187], v[222:223]
	v_pk_fma_f32 v[224:225], v[230:231], v[188:189], v[224:225]
	v_pk_fma_f32 v[226:227], v[230:231], v[190:191], v[226:227]
	v_pk_add_f32 v[8:9], v[8:9], v[220:221] neg_lo:[0,1] neg_hi:[0,1]
	v_pk_add_f32 v[10:11], v[10:11], v[222:223] neg_lo:[0,1] neg_hi:[0,1]
	v_pk_add_f32 v[4:5], v[4:5], v[224:225] neg_lo:[0,1] neg_hi:[0,1]
	v_pk_add_f32 v[6:7], v[6:7], v[226:227] neg_lo:[0,1] neg_hi:[0,1]
	v_pk_mul_f32 v[8:9], v[234:235], v[8:9]
	v_pk_mul_f32 v[10:11], v[234:235], v[10:11]
	v_pk_mul_f32 v[4:5], v[234:235], v[4:5]
	v_pk_mul_f32 v[6:7], v[234:235], v[6:7]
	v_cvt_pk_bf16_f32 v14, v8, v9
	v_cvt_pk_bf16_f32 v15, v10, v11
	v_cvt_pk_bf16_f32 v16, v4, v5
	v_cvt_pk_bf16_f32 v17, v6, v7
	v_lshl_add_u64 v[12:13], s[16:17], 0, v[28:29]
	v_lshl_add_u64 v[12:13], v[150:151], 1, v[12:13]
	global_store_dwordx4 v[12:13], v[14:17], off offset:256 sc1
	s_mov_b64 s[10:11], 0

.LBB0_371:
	v_lshl_add_u64 v[8:9], v[150:151], 1, v[32:33]
	v_cvt_pk_bf16_f32 v4, v12, v13
	v_cvt_pk_bf16_f32 v5, v14, v15
	v_cvt_pk_bf16_f32 v6, v16, v17
	v_cvt_pk_bf16_f32 v7, v18, v19
	global_store_dwordx4 v[8:9], v[4:7], off offset:256 sc1
	s_andn2_b64 vcc, exec, s[6:7]
	s_mov_b64 s[6:7], -1
	s_cbranch_vccnz .LBB0_143
	s_branch .LBB0_375
